# P1 sigmoid-family epilogue specialised per mode: 128 per-element selects on a wave-uniform mask removed, consumers read the chosen source pair directly; hazard pads re-derived
# speedup vs baseline: 1.0027x; 1.0027x over previous
.LBB0_204:
	s_cmp_lg_u64 s[42:43], 0
	s_cbranch_scc1 .Lsig_m1
	v_ashrrev_i32_e32 v0, 31, v202
	v_mul_lo_u32 v174, s57, v202
	v_mul_lo_u32 v0, s56, v0
	v_mad_u64_u32 v[176:177], s[10:11], s56, v202, 0
	v_add3_u32 v177, v177, v0, v174
	v_pk_mul_f32 v[174:175], v[128:129], s[8:9] op_sel_hi:[1,0]
	v_pk_mul_f32 v[204:205], v[126:127], s[8:9] op_sel_hi:[1,0]
	v_min_f32_e32 v174, 0x41e6d4ca, v174
	v_min_f32_e32 v203, 0x41e6d4ca, v204
	v_exp_f32_e32 v207, v203
	v_min_f32_e32 v203, 0x41e6d4ca, v205
	v_exp_f32_e32 v205, v174
	v_min_f32_e32 v174, 0x41e6d4ca, v175
	v_exp_f32_e32 v206, v203
	v_exp_f32_e32 v204, v174
	v_pk_add_f32 v[174:175], v[206:207], 1.0 op_sel_hi:[1,0]
	v_pk_add_f32 v[204:205], v[204:205], 1.0 op_sel_hi:[1,0]
	v_mul_f32_e32 v206, v175, v174
	v_mul_f32_e32 v207, v205, v204
	s_nop 0
	v_mul_f32_e32 v203, v206, v207
	v_rcp_f32_e32 v203, v203
	s_nop 0
	v_mul_f32_e32 v208, v207, v203
	v_mul_f32_e32 v206, v206, v203
	v_pk_mul_f32 v[174:175], v[174:175], v[208:209] op_sel_hi:[1,0]
	v_pk_mul_f32 v[204:205], v[204:205], v[206:207] op_sel_hi:[1,0]
	s_waitcnt vmcnt(0)
	v_pk_mul_f32 v[174:175], v[142:143], v[174:175]
	v_pk_mul_f32 v[206:207], v[122:123], s[8:9] op_sel_hi:[1,0]
	s_nop 0
	v_min_f32_e32 v203, 0x41e6d4ca, v206
	v_pk_mul_f32 v[208:209], v[144:145], v[204:205]
	v_pk_mul_f32 v[204:205], v[124:125], s[8:9] op_sel_hi:[1,0]
	v_exp_f32_e32 v211, v203
	v_min_f32_e32 v203, 0x41e6d4ca, v207
	v_exp_f32_e32 v210, v203
	v_min_f32_e32 v203, 0x41e6d4ca, v204
	v_exp_f32_e32 v207, v203
	v_min_f32_e32 v203, 0x41e6d4ca, v205
	v_exp_f32_e32 v206, v203
	v_pk_add_f32 v[204:205], v[210:211], 1.0 op_sel_hi:[1,0]
	v_pk_add_f32 v[206:207], v[206:207], 1.0 op_sel_hi:[1,0]
	v_mul_f32_e32 v210, v205, v204
	v_mul_f32_e32 v211, v207, v206
	s_nop 0
	v_mul_f32_e32 v203, v210, v211
	v_rcp_f32_e32 v203, v203
	s_nop 0
	v_mul_f32_e32 v212, v211, v203
	v_mul_f32_e32 v210, v210, v203
	v_pk_mul_f32 v[204:205], v[204:205], v[212:213] op_sel_hi:[1,0]
	v_pk_mul_f32 v[206:207], v[206:207], v[210:211] op_sel_hi:[1,0]
	v_pk_mul_f32 v[212:213], v[140:141], v[206:207]
	v_pk_mul_f32 v[206:207], v[138:139], v[204:205]
	v_cvt_pk_bf16_f32 v204, v174, v175
	v_cvt_pk_bf16_f32 v205, v208, v209
	v_lshl_add_u64 v[174:175], v[170:171], 1, s[86:87]
	v_lshlrev_b64 v[208:209], 1, v[176:177]
	v_cvt_pk_bf16_f32 v206, v206, v207
	v_cvt_pk_bf16_f32 v207, v212, v213
	v_lshl_add_u64 v[176:177], v[174:175], 0, v[208:209]
	global_store_dwordx4 v[176:177], v[204:207], off
	v_pk_mul_f32 v[176:177], v[120:121], s[8:9] op_sel_hi:[1,0]
	s_nop 0
	v_pk_mul_f32 v[204:205], v[118:119], s[8:9] op_sel_hi:[1,0]
	v_min_f32_e32 v176, 0x41e6d4ca, v176
	v_min_f32_e32 v203, 0x41e6d4ca, v204
	v_exp_f32_e32 v207, v203
	v_min_f32_e32 v203, 0x41e6d4ca, v205
	v_exp_f32_e32 v205, v176
	v_min_f32_e32 v176, 0x41e6d4ca, v177
	v_exp_f32_e32 v206, v203
	v_exp_f32_e32 v204, v176
	v_pk_add_f32 v[176:177], v[206:207], 1.0 op_sel_hi:[1,0]
	v_pk_add_f32 v[204:205], v[204:205], 1.0 op_sel_hi:[1,0]
	v_mul_f32_e32 v206, v177, v176
	v_mul_f32_e32 v207, v205, v204
	s_nop 0
	v_mul_f32_e32 v203, v206, v207
	v_rcp_f32_e32 v203, v203
	s_nop 0
	v_mul_f32_e32 v210, v207, v203
	v_mul_f32_e32 v206, v206, v203
	v_pk_mul_f32 v[176:177], v[176:177], v[210:211] op_sel_hi:[1,0]
	v_pk_mul_f32 v[204:205], v[204:205], v[206:207] op_sel_hi:[1,0]
	v_pk_mul_f32 v[176:177], v[134:135], v[176:177]
	v_pk_mul_f32 v[206:207], v[114:115], s[8:9] op_sel_hi:[1,0]
	s_nop 0
	v_min_f32_e32 v203, 0x41e6d4ca, v206
	v_pk_mul_f32 v[210:211], v[136:137], v[204:205]
	v_pk_mul_f32 v[204:205], v[116:117], s[8:9] op_sel_hi:[1,0]
	v_exp_f32_e32 v213, v203
	v_min_f32_e32 v203, 0x41e6d4ca, v207
	v_exp_f32_e32 v212, v203
	v_min_f32_e32 v203, 0x41e6d4ca, v204
	v_exp_f32_e32 v207, v203
	v_min_f32_e32 v203, 0x41e6d4ca, v205
	v_exp_f32_e32 v206, v203
	v_pk_add_f32 v[204:205], v[212:213], 1.0 op_sel_hi:[1,0]
	v_pk_add_f32 v[206:207], v[206:207], 1.0 op_sel_hi:[1,0]
	v_mul_f32_e32 v212, v205, v204
	v_mul_f32_e32 v213, v207, v206
	s_nop 0
	v_mul_f32_e32 v203, v212, v213
	v_rcp_f32_e32 v203, v203
	s_nop 0
	v_mul_f32_e32 v216, v213, v203
	v_mul_f32_e32 v212, v212, v203
	v_pk_mul_f32 v[204:205], v[204:205], v[216:217] op_sel_hi:[1,0]
	v_pk_mul_f32 v[206:207], v[206:207], v[212:213] op_sel_hi:[1,0]
	v_pk_mul_f32 v[216:217], v[132:133], v[206:207]
	v_pk_mul_f32 v[206:207], v[130:131], v[204:205]
	v_cvt_pk_bf16_f32 v204, v176, v177
	v_lshl_add_u64 v[176:177], v[172:173], 1, s[86:87]
	v_cvt_pk_bf16_f32 v205, v210, v211
	v_cvt_pk_bf16_f32 v206, v206, v207
	v_cvt_pk_bf16_f32 v207, v216, v217
	v_lshl_add_u64 v[208:209], v[176:177], 0, v[208:209]
	global_store_dwordx4 v[208:209], v[204:207], off
	v_or_b32_e32 v203, 16, v202
	v_mad_u64_u32 v[208:209], s[10:11], s56, v203, 0
	v_pk_mul_f32 v[206:207], v[110:111], s[8:9] op_sel_hi:[1,0]
	v_mul_lo_u32 v204, s57, v203
	v_min_f32_e32 v203, 0x41e6d4ca, v206
	v_add3_u32 v209, v209, v0, v204
	v_pk_mul_f32 v[204:205], v[112:113], s[8:9] op_sel_hi:[1,0]
	v_exp_f32_e32 v211, v203
	v_min_f32_e32 v203, 0x41e6d4ca, v207
	v_exp_f32_e32 v210, v203
	v_min_f32_e32 v203, 0x41e6d4ca, v204
	v_exp_f32_e32 v207, v203
	v_min_f32_e32 v203, 0x41e6d4ca, v205
	v_exp_f32_e32 v206, v203
	v_pk_add_f32 v[204:205], v[210:211], 1.0 op_sel_hi:[1,0]
	v_lshlrev_b64 v[208:209], 1, v[208:209]
	v_pk_add_f32 v[206:207], v[206:207], 1.0 op_sel_hi:[1,0]
	v_mul_f32_e32 v210, v205, v204
	v_mul_f32_e32 v211, v207, v206
	s_nop 0
	v_mul_f32_e32 v203, v210, v211
	v_rcp_f32_e32 v203, v203
	s_nop 0
	v_mul_f32_e32 v212, v211, v203
	v_mul_f32_e32 v210, v210, v203
	v_pk_mul_f32 v[204:205], v[204:205], v[212:213] op_sel_hi:[1,0]
	v_pk_mul_f32 v[206:207], v[206:207], v[210:211] op_sel_hi:[1,0]
	v_pk_mul_f32 v[206:207], v[144:145], v[206:207]
	v_pk_mul_f32 v[212:213], v[106:107], s[8:9] op_sel_hi:[1,0]
	s_nop 0
	v_min_f32_e32 v203, 0x41e6d4ca, v212
	v_pk_mul_f32 v[204:205], v[142:143], v[204:205]
	v_pk_mul_f32 v[210:211], v[108:109], s[8:9] op_sel_hi:[1,0]
	v_exp_f32_e32 v217, v203
	v_min_f32_e32 v203, 0x41e6d4ca, v213
	v_exp_f32_e32 v216, v203
	v_min_f32_e32 v203, 0x41e6d4ca, v210
	v_exp_f32_e32 v213, v203
	v_min_f32_e32 v203, 0x41e6d4ca, v211
	v_exp_f32_e32 v212, v203
	v_pk_add_f32 v[210:211], v[216:217], 1.0 op_sel_hi:[1,0]
	v_cvt_pk_bf16_f32 v204, v204, v205
	v_pk_add_f32 v[212:213], v[212:213], 1.0 op_sel_hi:[1,0]
	v_mul_f32_e32 v216, v211, v210
	v_mul_f32_e32 v217, v213, v212
	v_cvt_pk_bf16_f32 v205, v206, v207
	v_mul_f32_e32 v203, v216, v217
	v_rcp_f32_e32 v203, v203
	s_nop 0
	v_mul_f32_e32 v218, v217, v203
	v_mul_f32_e32 v216, v216, v203
	v_pk_mul_f32 v[210:211], v[210:211], v[218:219] op_sel_hi:[1,0]
	v_pk_mul_f32 v[212:213], v[212:213], v[216:217] op_sel_hi:[1,0]
	v_pk_mul_f32 v[212:213], v[140:141], v[212:213]
	v_pk_mul_f32 v[210:211], v[138:139], v[210:211]
	v_cvt_pk_bf16_f32 v207, v212, v213
	v_cvt_pk_bf16_f32 v206, v210, v211
	v_lshl_add_u64 v[210:211], v[174:175], 0, v[208:209]
	global_store_dwordx4 v[210:211], v[204:207], off
	v_lshl_add_u64 v[208:209], v[176:177], 0, v[208:209]
	s_nop 0
	v_pk_mul_f32 v[206:207], v[102:103], s[8:9] op_sel_hi:[1,0]
	v_pk_mul_f32 v[204:205], v[104:105], s[8:9] op_sel_hi:[1,0]
	v_min_f32_e32 v203, 0x41e6d4ca, v206
	v_exp_f32_e32 v211, v203
	v_min_f32_e32 v203, 0x41e6d4ca, v207
	v_exp_f32_e32 v210, v203
	v_min_f32_e32 v203, 0x41e6d4ca, v204
	v_exp_f32_e32 v207, v203
	v_min_f32_e32 v203, 0x41e6d4ca, v205
	v_exp_f32_e32 v206, v203
	v_pk_add_f32 v[204:205], v[210:211], 1.0 op_sel_hi:[1,0]
	v_pk_add_f32 v[206:207], v[206:207], 1.0 op_sel_hi:[1,0]
	v_mul_f32_e32 v210, v205, v204
	v_mul_f32_e32 v211, v207, v206
	s_nop 0
	v_mul_f32_e32 v203, v210, v211
	v_rcp_f32_e32 v203, v203
	s_nop 0
	v_mul_f32_e32 v212, v211, v203
	v_mul_f32_e32 v210, v210, v203
	v_pk_mul_f32 v[204:205], v[204:205], v[212:213] op_sel_hi:[1,0]
	v_pk_mul_f32 v[206:207], v[206:207], v[210:211] op_sel_hi:[1,0]
	v_pk_mul_f32 v[206:207], v[136:137], v[206:207]
	v_pk_mul_f32 v[212:213], v[98:99], s[8:9] op_sel_hi:[1,0]
	s_nop 0
	v_min_f32_e32 v203, 0x41e6d4ca, v212
	v_pk_mul_f32 v[204:205], v[134:135], v[204:205]
	v_pk_mul_f32 v[210:211], v[100:101], s[8:9] op_sel_hi:[1,0]
	v_exp_f32_e32 v217, v203
	v_min_f32_e32 v203, 0x41e6d4ca, v213
	v_exp_f32_e32 v216, v203
	v_min_f32_e32 v203, 0x41e6d4ca, v210
	v_exp_f32_e32 v213, v203
	v_min_f32_e32 v203, 0x41e6d4ca, v211
	v_exp_f32_e32 v212, v203
	v_pk_add_f32 v[210:211], v[216:217], 1.0 op_sel_hi:[1,0]
	v_cvt_pk_bf16_f32 v204, v204, v205
	v_pk_add_f32 v[212:213], v[212:213], 1.0 op_sel_hi:[1,0]
	v_mul_f32_e32 v216, v211, v210
	v_mul_f32_e32 v217, v213, v212
	v_cvt_pk_bf16_f32 v205, v206, v207
	v_mul_f32_e32 v203, v216, v217
	v_rcp_f32_e32 v203, v203
	s_nop 0
	v_mul_f32_e32 v218, v217, v203
	v_mul_f32_e32 v216, v216, v203
	v_pk_mul_f32 v[210:211], v[210:211], v[218:219] op_sel_hi:[1,0]
	v_pk_mul_f32 v[212:213], v[212:213], v[216:217] op_sel_hi:[1,0]
	v_pk_mul_f32 v[212:213], v[132:133], v[212:213]
	v_pk_mul_f32 v[210:211], v[130:131], v[210:211]
	v_cvt_pk_bf16_f32 v207, v212, v213
	v_cvt_pk_bf16_f32 v206, v210, v211
	global_store_dwordx4 v[208:209], v[204:207], off
	v_or_b32_e32 v203, 32, v202
	v_mad_u64_u32 v[208:209], s[10:11], s56, v203, 0
	v_pk_mul_f32 v[206:207], v[94:95], s[8:9] op_sel_hi:[1,0]
	v_mul_lo_u32 v204, s57, v203
	v_min_f32_e32 v203, 0x41e6d4ca, v206
	v_add3_u32 v209, v209, v0, v204
	v_pk_mul_f32 v[204:205], v[96:97], s[8:9] op_sel_hi:[1,0]
	v_exp_f32_e32 v211, v203
	v_min_f32_e32 v203, 0x41e6d4ca, v207
	v_exp_f32_e32 v210, v203
	v_min_f32_e32 v203, 0x41e6d4ca, v204
	v_exp_f32_e32 v207, v203
	v_min_f32_e32 v203, 0x41e6d4ca, v205
	v_exp_f32_e32 v206, v203
	v_pk_add_f32 v[204:205], v[210:211], 1.0 op_sel_hi:[1,0]
	v_lshlrev_b64 v[208:209], 1, v[208:209]
	v_pk_add_f32 v[206:207], v[206:207], 1.0 op_sel_hi:[1,0]
	v_mul_f32_e32 v210, v205, v204
	v_mul_f32_e32 v211, v207, v206
	s_nop 0
	v_mul_f32_e32 v203, v210, v211
	v_rcp_f32_e32 v203, v203
	s_nop 0
	v_mul_f32_e32 v212, v211, v203
	v_mul_f32_e32 v210, v210, v203
	v_pk_mul_f32 v[204:205], v[204:205], v[212:213] op_sel_hi:[1,0]
	v_pk_mul_f32 v[206:207], v[206:207], v[210:211] op_sel_hi:[1,0]
	v_pk_mul_f32 v[206:207], v[144:145], v[206:207]
	v_pk_mul_f32 v[212:213], v[90:91], s[8:9] op_sel_hi:[1,0]
	s_nop 0
	v_min_f32_e32 v203, 0x41e6d4ca, v212
	v_pk_mul_f32 v[204:205], v[142:143], v[204:205]
	v_pk_mul_f32 v[210:211], v[92:93], s[8:9] op_sel_hi:[1,0]
	v_exp_f32_e32 v217, v203
	v_min_f32_e32 v203, 0x41e6d4ca, v213
	v_exp_f32_e32 v216, v203
	v_min_f32_e32 v203, 0x41e6d4ca, v210
	v_exp_f32_e32 v213, v203
	v_min_f32_e32 v203, 0x41e6d4ca, v211
	v_exp_f32_e32 v212, v203
	v_pk_add_f32 v[210:211], v[216:217], 1.0 op_sel_hi:[1,0]
	v_cvt_pk_bf16_f32 v204, v204, v205
	v_pk_add_f32 v[212:213], v[212:213], 1.0 op_sel_hi:[1,0]
	v_mul_f32_e32 v216, v211, v210
	v_mul_f32_e32 v217, v213, v212
	v_cvt_pk_bf16_f32 v205, v206, v207
	v_mul_f32_e32 v203, v216, v217
	v_rcp_f32_e32 v203, v203
	s_nop 0
	v_mul_f32_e32 v218, v217, v203
	v_mul_f32_e32 v216, v216, v203
	v_pk_mul_f32 v[210:211], v[210:211], v[218:219] op_sel_hi:[1,0]
	v_pk_mul_f32 v[212:213], v[212:213], v[216:217] op_sel_hi:[1,0]
	v_pk_mul_f32 v[212:213], v[140:141], v[212:213]
	v_pk_mul_f32 v[210:211], v[138:139], v[210:211]
	v_cvt_pk_bf16_f32 v207, v212, v213
	v_cvt_pk_bf16_f32 v206, v210, v211
	v_lshl_add_u64 v[210:211], v[174:175], 0, v[208:209]
	global_store_dwordx4 v[210:211], v[204:207], off
	v_lshl_add_u64 v[208:209], v[176:177], 0, v[208:209]
	s_nop 0
	v_pk_mul_f32 v[206:207], v[86:87], s[8:9] op_sel_hi:[1,0]
	v_pk_mul_f32 v[204:205], v[88:89], s[8:9] op_sel_hi:[1,0]
	v_min_f32_e32 v203, 0x41e6d4ca, v206
	v_exp_f32_e32 v211, v203
	v_min_f32_e32 v203, 0x41e6d4ca, v207
	v_exp_f32_e32 v210, v203
	v_min_f32_e32 v203, 0x41e6d4ca, v204
	v_exp_f32_e32 v207, v203
	v_min_f32_e32 v203, 0x41e6d4ca, v205
	v_exp_f32_e32 v206, v203
	v_pk_add_f32 v[204:205], v[210:211], 1.0 op_sel_hi:[1,0]
	v_pk_add_f32 v[206:207], v[206:207], 1.0 op_sel_hi:[1,0]
	v_mul_f32_e32 v210, v205, v204
	v_mul_f32_e32 v211, v207, v206
	s_nop 0
	v_mul_f32_e32 v203, v210, v211
	v_rcp_f32_e32 v203, v203
	s_nop 0
	v_mul_f32_e32 v212, v211, v203
	v_mul_f32_e32 v210, v210, v203
	v_pk_mul_f32 v[204:205], v[204:205], v[212:213] op_sel_hi:[1,0]
	v_pk_mul_f32 v[206:207], v[206:207], v[210:211] op_sel_hi:[1,0]
	v_pk_mul_f32 v[206:207], v[136:137], v[206:207]
	v_pk_mul_f32 v[212:213], v[82:83], s[8:9] op_sel_hi:[1,0]
	s_nop 0
	v_min_f32_e32 v203, 0x41e6d4ca, v212
	v_pk_mul_f32 v[204:205], v[134:135], v[204:205]
	v_pk_mul_f32 v[210:211], v[84:85], s[8:9] op_sel_hi:[1,0]
	v_exp_f32_e32 v217, v203
	v_min_f32_e32 v203, 0x41e6d4ca, v213
	v_exp_f32_e32 v216, v203
	v_min_f32_e32 v203, 0x41e6d4ca, v210
	v_exp_f32_e32 v213, v203
	v_min_f32_e32 v203, 0x41e6d4ca, v211
	v_exp_f32_e32 v212, v203
	v_pk_add_f32 v[210:211], v[216:217], 1.0 op_sel_hi:[1,0]
	v_cvt_pk_bf16_f32 v204, v204, v205
	v_pk_add_f32 v[212:213], v[212:213], 1.0 op_sel_hi:[1,0]
	v_mul_f32_e32 v216, v211, v210
	v_mul_f32_e32 v217, v213, v212
	v_cvt_pk_bf16_f32 v205, v206, v207
	v_mul_f32_e32 v203, v216, v217
	v_rcp_f32_e32 v203, v203
	s_nop 0
	v_mul_f32_e32 v218, v217, v203
	v_mul_f32_e32 v216, v216, v203
	v_pk_mul_f32 v[210:211], v[210:211], v[218:219] op_sel_hi:[1,0]
	v_pk_mul_f32 v[212:213], v[212:213], v[216:217] op_sel_hi:[1,0]
	v_pk_mul_f32 v[212:213], v[132:133], v[212:213]
	v_pk_mul_f32 v[210:211], v[130:131], v[210:211]
	v_cvt_pk_bf16_f32 v207, v212, v213
	v_cvt_pk_bf16_f32 v206, v210, v211
	v_or_b32_e32 v203, 48, v202
	global_store_dwordx4 v[208:209], v[204:207], off
	v_mad_u64_u32 v[208:209], s[10:11], s56, v203, 0
	s_nop 0
	v_mul_lo_u32 v204, s57, v203
	v_pk_mul_f32 v[206:207], v[78:79], s[8:9] op_sel_hi:[1,0]
	v_add3_u32 v209, v209, v0, v204
	v_min_f32_e32 v0, 0x41e6d4ca, v206
	v_pk_mul_f32 v[204:205], v[80:81], s[8:9] op_sel_hi:[1,0]
	v_exp_f32_e32 v211, v0
	v_min_f32_e32 v0, 0x41e6d4ca, v207
	v_exp_f32_e32 v210, v0
	v_min_f32_e32 v0, 0x41e6d4ca, v204
	v_exp_f32_e32 v207, v0
	v_min_f32_e32 v0, 0x41e6d4ca, v205
	v_exp_f32_e32 v206, v0
	v_pk_add_f32 v[204:205], v[210:211], 1.0 op_sel_hi:[1,0]
	v_lshlrev_b64 v[208:209], 1, v[208:209]
	v_pk_add_f32 v[206:207], v[206:207], 1.0 op_sel_hi:[1,0]
	v_mul_f32_e32 v210, v205, v204
	v_mul_f32_e32 v211, v207, v206
	v_mul_f32_e32 v0, v210, v211
	v_rcp_f32_e32 v203, v0
	s_nop 0
	v_mul_f32_e32 v210, v210, v203
	v_pk_mul_f32 v[206:207], v[206:207], v[210:211] op_sel_hi:[1,0]
	v_mul_f32_e32 v0, v211, v203
	v_pk_mul_f32 v[206:207], v[144:145], v[206:207]
	v_pk_mul_f32 v[212:213], v[74:75], s[8:9] op_sel_hi:[1,0]
	v_pk_mul_f32 v[204:205], v[204:205], v[0:1] op_sel_hi:[1,0]
	v_min_f32_e32 v0, 0x41e6d4ca, v212
	v_pk_mul_f32 v[204:205], v[142:143], v[204:205]
	v_pk_mul_f32 v[210:211], v[76:77], s[8:9] op_sel_hi:[1,0]
	v_exp_f32_e32 v217, v0
	v_min_f32_e32 v0, 0x41e6d4ca, v213
	v_exp_f32_e32 v216, v0
	v_min_f32_e32 v0, 0x41e6d4ca, v210
	v_exp_f32_e32 v213, v0
	v_min_f32_e32 v0, 0x41e6d4ca, v211
	v_exp_f32_e32 v212, v0
	v_pk_add_f32 v[210:211], v[216:217], 1.0 op_sel_hi:[1,0]
	v_cvt_pk_bf16_f32 v204, v204, v205
	v_pk_add_f32 v[212:213], v[212:213], 1.0 op_sel_hi:[1,0]
	v_mul_f32_e32 v216, v211, v210
	v_mul_f32_e32 v217, v213, v212
	v_mul_f32_e32 v0, v216, v217
	v_rcp_f32_e32 v203, v0
	v_cvt_pk_bf16_f32 v205, v206, v207
	v_mul_f32_e32 v0, v217, v203
	v_mul_f32_e32 v216, v216, v203
	v_pk_mul_f32 v[210:211], v[210:211], v[0:1] op_sel_hi:[1,0]
	v_pk_mul_f32 v[212:213], v[212:213], v[216:217] op_sel_hi:[1,0]
	v_pk_mul_f32 v[212:213], v[140:141], v[212:213]
	v_pk_mul_f32 v[210:211], v[138:139], v[210:211]
	v_cvt_pk_bf16_f32 v207, v212, v213
	v_cvt_pk_bf16_f32 v206, v210, v211
	v_lshl_add_u64 v[210:211], v[174:175], 0, v[208:209]
	global_store_dwordx4 v[210:211], v[204:207], off
	v_lshl_add_u64 v[208:209], v[176:177], 0, v[208:209]
	s_nop 0
	v_pk_mul_f32 v[206:207], v[70:71], s[8:9] op_sel_hi:[1,0]
	v_pk_mul_f32 v[204:205], v[72:73], s[8:9] op_sel_hi:[1,0]
	v_min_f32_e32 v0, 0x41e6d4ca, v206
	v_exp_f32_e32 v211, v0
	v_min_f32_e32 v0, 0x41e6d4ca, v207
	v_exp_f32_e32 v210, v0
	v_min_f32_e32 v0, 0x41e6d4ca, v204
	v_exp_f32_e32 v207, v0
	v_min_f32_e32 v0, 0x41e6d4ca, v205
	v_exp_f32_e32 v206, v0
	v_pk_add_f32 v[204:205], v[210:211], 1.0 op_sel_hi:[1,0]
	v_pk_add_f32 v[206:207], v[206:207], 1.0 op_sel_hi:[1,0]
	v_mul_f32_e32 v210, v205, v204
	v_mul_f32_e32 v211, v207, v206
	v_mul_f32_e32 v0, v210, v211
	v_rcp_f32_e32 v203, v0
	s_nop 0
	v_mul_f32_e32 v210, v210, v203
	v_pk_mul_f32 v[206:207], v[206:207], v[210:211] op_sel_hi:[1,0]
	v_mul_f32_e32 v0, v211, v203
	v_pk_mul_f32 v[206:207], v[136:137], v[206:207]
	v_pk_mul_f32 v[212:213], v[66:67], s[8:9] op_sel_hi:[1,0]
	v_pk_mul_f32 v[204:205], v[204:205], v[0:1] op_sel_hi:[1,0]
	v_min_f32_e32 v0, 0x41e6d4ca, v212
	v_pk_mul_f32 v[204:205], v[134:135], v[204:205]
	v_pk_mul_f32 v[210:211], v[68:69], s[8:9] op_sel_hi:[1,0]
	v_exp_f32_e32 v217, v0
	v_min_f32_e32 v0, 0x41e6d4ca, v213
	v_exp_f32_e32 v216, v0
	v_min_f32_e32 v0, 0x41e6d4ca, v210
	v_exp_f32_e32 v213, v0
	v_min_f32_e32 v0, 0x41e6d4ca, v211
	v_exp_f32_e32 v212, v0
	v_pk_add_f32 v[210:211], v[216:217], 1.0 op_sel_hi:[1,0]
	v_cvt_pk_bf16_f32 v204, v204, v205
	v_pk_add_f32 v[212:213], v[212:213], 1.0 op_sel_hi:[1,0]
	v_mul_f32_e32 v216, v211, v210
	v_mul_f32_e32 v217, v213, v212
	v_mul_f32_e32 v0, v216, v217
	v_rcp_f32_e32 v203, v0
	v_cvt_pk_bf16_f32 v205, v206, v207
	v_mul_f32_e32 v0, v217, v203
	v_mul_f32_e32 v216, v216, v203
	v_pk_mul_f32 v[210:211], v[210:211], v[0:1] op_sel_hi:[1,0]
	v_pk_mul_f32 v[212:213], v[212:213], v[216:217] op_sel_hi:[1,0]
	v_pk_mul_f32 v[212:213], v[132:133], v[212:213]
	v_pk_mul_f32 v[210:211], v[130:131], v[210:211]
	v_cvt_pk_bf16_f32 v207, v212, v213
	v_cvt_pk_bf16_f32 v206, v210, v211
	v_add_u32_e32 v0, 0x80, v202
	global_store_dwordx4 v[208:209], v[204:207], off
	v_ashrrev_i32_e32 v203, 31, v0
	v_mul_lo_u32 v203, s56, v203
	v_pk_mul_f32 v[206:207], v[62:63], s[8:9] op_sel_hi:[1,0]
	v_mul_lo_u32 v204, s57, v0
	v_mad_u64_u32 v[208:209], s[10:11], s56, v0, 0
	v_min_f32_e32 v0, 0x41e6d4ca, v206
	v_add3_u32 v209, v209, v203, v204
	v_pk_mul_f32 v[204:205], v[64:65], s[8:9] op_sel_hi:[1,0]
	v_exp_f32_e32 v211, v0
	v_min_f32_e32 v0, 0x41e6d4ca, v207
	v_exp_f32_e32 v210, v0
	v_min_f32_e32 v0, 0x41e6d4ca, v204
	v_exp_f32_e32 v207, v0
	v_min_f32_e32 v0, 0x41e6d4ca, v205
	v_exp_f32_e32 v206, v0
	v_pk_add_f32 v[204:205], v[210:211], 1.0 op_sel_hi:[1,0]
	v_lshlrev_b64 v[208:209], 1, v[208:209]
	v_pk_add_f32 v[206:207], v[206:207], 1.0 op_sel_hi:[1,0]
	v_mul_f32_e32 v210, v205, v204
	v_mul_f32_e32 v211, v207, v206
	v_mul_f32_e32 v0, v210, v211
	v_rcp_f32_e32 v203, v0
	s_nop 0
	v_mul_f32_e32 v210, v210, v203
	v_pk_mul_f32 v[206:207], v[206:207], v[210:211] op_sel_hi:[1,0]
	v_mul_f32_e32 v0, v211, v203
	v_pk_mul_f32 v[206:207], v[144:145], v[206:207]
	v_pk_mul_f32 v[212:213], v[58:59], s[8:9] op_sel_hi:[1,0]
	v_pk_mul_f32 v[204:205], v[204:205], v[0:1] op_sel_hi:[1,0]
	v_min_f32_e32 v0, 0x41e6d4ca, v212
	v_pk_mul_f32 v[204:205], v[142:143], v[204:205]
	v_pk_mul_f32 v[210:211], v[60:61], s[8:9] op_sel_hi:[1,0]
	v_exp_f32_e32 v217, v0
	v_min_f32_e32 v0, 0x41e6d4ca, v213
	v_exp_f32_e32 v216, v0
	v_min_f32_e32 v0, 0x41e6d4ca, v210
	v_exp_f32_e32 v213, v0
	v_min_f32_e32 v0, 0x41e6d4ca, v211
	v_exp_f32_e32 v212, v0
	v_pk_add_f32 v[210:211], v[216:217], 1.0 op_sel_hi:[1,0]
	v_cvt_pk_bf16_f32 v204, v204, v205
	v_pk_add_f32 v[212:213], v[212:213], 1.0 op_sel_hi:[1,0]
	v_mul_f32_e32 v216, v211, v210
	v_mul_f32_e32 v217, v213, v212
	v_mul_f32_e32 v0, v216, v217
	v_rcp_f32_e32 v203, v0
	v_cvt_pk_bf16_f32 v205, v206, v207
	v_mul_f32_e32 v0, v217, v203
	v_mul_f32_e32 v216, v216, v203
	v_pk_mul_f32 v[210:211], v[210:211], v[0:1] op_sel_hi:[1,0]
	v_pk_mul_f32 v[212:213], v[212:213], v[216:217] op_sel_hi:[1,0]
	v_pk_mul_f32 v[212:213], v[140:141], v[212:213]
	v_pk_mul_f32 v[210:211], v[138:139], v[210:211]
	v_cvt_pk_bf16_f32 v207, v212, v213
	v_cvt_pk_bf16_f32 v206, v210, v211
	v_lshl_add_u64 v[210:211], v[174:175], 0, v[208:209]
	global_store_dwordx4 v[210:211], v[204:207], off
	v_lshl_add_u64 v[208:209], v[176:177], 0, v[208:209]
	s_nop 0
	v_pk_mul_f32 v[206:207], v[54:55], s[8:9] op_sel_hi:[1,0]
	v_pk_mul_f32 v[204:205], v[56:57], s[8:9] op_sel_hi:[1,0]
	v_min_f32_e32 v0, 0x41e6d4ca, v206
	v_exp_f32_e32 v211, v0
	v_min_f32_e32 v0, 0x41e6d4ca, v207
	v_exp_f32_e32 v210, v0
	v_min_f32_e32 v0, 0x41e6d4ca, v204
	v_exp_f32_e32 v207, v0
	v_min_f32_e32 v0, 0x41e6d4ca, v205
	v_exp_f32_e32 v206, v0
	v_pk_add_f32 v[204:205], v[210:211], 1.0 op_sel_hi:[1,0]
	v_pk_add_f32 v[206:207], v[206:207], 1.0 op_sel_hi:[1,0]
	v_mul_f32_e32 v210, v205, v204
	v_mul_f32_e32 v211, v207, v206
	v_mul_f32_e32 v0, v210, v211
	v_rcp_f32_e32 v203, v0
	s_nop 0
	v_mul_f32_e32 v210, v210, v203
	v_pk_mul_f32 v[206:207], v[206:207], v[210:211] op_sel_hi:[1,0]
	v_mul_f32_e32 v0, v211, v203
	v_pk_mul_f32 v[206:207], v[136:137], v[206:207]
	v_pk_mul_f32 v[212:213], v[50:51], s[8:9] op_sel_hi:[1,0]
	v_pk_mul_f32 v[204:205], v[204:205], v[0:1] op_sel_hi:[1,0]
	v_min_f32_e32 v0, 0x41e6d4ca, v212
	v_pk_mul_f32 v[204:205], v[134:135], v[204:205]
	v_pk_mul_f32 v[210:211], v[52:53], s[8:9] op_sel_hi:[1,0]
	v_exp_f32_e32 v217, v0
	v_min_f32_e32 v0, 0x41e6d4ca, v213
	v_exp_f32_e32 v216, v0
	v_min_f32_e32 v0, 0x41e6d4ca, v210
	v_exp_f32_e32 v213, v0
	v_min_f32_e32 v0, 0x41e6d4ca, v211
	v_exp_f32_e32 v212, v0
	v_pk_add_f32 v[210:211], v[216:217], 1.0 op_sel_hi:[1,0]
	v_cvt_pk_bf16_f32 v204, v204, v205
	v_pk_add_f32 v[212:213], v[212:213], 1.0 op_sel_hi:[1,0]
	v_mul_f32_e32 v216, v211, v210
	v_mul_f32_e32 v217, v213, v212
	v_mul_f32_e32 v0, v216, v217
	v_rcp_f32_e32 v203, v0
	v_cvt_pk_bf16_f32 v205, v206, v207
	v_mul_f32_e32 v0, v217, v203
	v_mul_f32_e32 v216, v216, v203
	v_pk_mul_f32 v[210:211], v[210:211], v[0:1] op_sel_hi:[1,0]
	v_pk_mul_f32 v[212:213], v[212:213], v[216:217] op_sel_hi:[1,0]
	v_pk_mul_f32 v[212:213], v[132:133], v[212:213]
	v_pk_mul_f32 v[210:211], v[130:131], v[210:211]
	v_cvt_pk_bf16_f32 v207, v212, v213
	v_cvt_pk_bf16_f32 v206, v210, v211
	v_add_u32_e32 v0, 0x90, v202
	global_store_dwordx4 v[208:209], v[204:207], off
	v_ashrrev_i32_e32 v203, 31, v0
	v_mul_lo_u32 v203, s56, v203
	v_pk_mul_f32 v[206:207], v[46:47], s[8:9] op_sel_hi:[1,0]
	v_mul_lo_u32 v204, s57, v0
	v_mad_u64_u32 v[208:209], s[10:11], s56, v0, 0
	v_min_f32_e32 v0, 0x41e6d4ca, v206
	v_add3_u32 v209, v209, v203, v204
	v_pk_mul_f32 v[204:205], v[48:49], s[8:9] op_sel_hi:[1,0]
	v_exp_f32_e32 v211, v0
	v_min_f32_e32 v0, 0x41e6d4ca, v207
	v_exp_f32_e32 v210, v0
	v_min_f32_e32 v0, 0x41e6d4ca, v204
	v_exp_f32_e32 v207, v0
	v_min_f32_e32 v0, 0x41e6d4ca, v205
	v_exp_f32_e32 v206, v0
	v_pk_add_f32 v[204:205], v[210:211], 1.0 op_sel_hi:[1,0]
	v_lshlrev_b64 v[208:209], 1, v[208:209]
	v_pk_add_f32 v[206:207], v[206:207], 1.0 op_sel_hi:[1,0]
	v_mul_f32_e32 v210, v205, v204
	v_mul_f32_e32 v211, v207, v206
	v_mul_f32_e32 v0, v210, v211
	v_rcp_f32_e32 v203, v0
	s_nop 0
	v_mul_f32_e32 v210, v210, v203
	v_pk_mul_f32 v[206:207], v[206:207], v[210:211] op_sel_hi:[1,0]
	v_mul_f32_e32 v0, v211, v203
	v_pk_mul_f32 v[206:207], v[144:145], v[206:207]
	v_pk_mul_f32 v[212:213], v[42:43], s[8:9] op_sel_hi:[1,0]
	v_pk_mul_f32 v[204:205], v[204:205], v[0:1] op_sel_hi:[1,0]
	v_min_f32_e32 v0, 0x41e6d4ca, v212
	v_pk_mul_f32 v[204:205], v[142:143], v[204:205]
	v_pk_mul_f32 v[210:211], v[44:45], s[8:9] op_sel_hi:[1,0]
	v_exp_f32_e32 v217, v0
	v_min_f32_e32 v0, 0x41e6d4ca, v213
	v_exp_f32_e32 v216, v0
	v_min_f32_e32 v0, 0x41e6d4ca, v210
	v_exp_f32_e32 v213, v0
	v_min_f32_e32 v0, 0x41e6d4ca, v211
	v_exp_f32_e32 v212, v0
	v_pk_add_f32 v[210:211], v[216:217], 1.0 op_sel_hi:[1,0]
	v_cvt_pk_bf16_f32 v204, v204, v205
	v_pk_add_f32 v[212:213], v[212:213], 1.0 op_sel_hi:[1,0]
	v_mul_f32_e32 v216, v211, v210
	v_mul_f32_e32 v217, v213, v212
	v_mul_f32_e32 v0, v216, v217
	v_rcp_f32_e32 v203, v0
	v_cvt_pk_bf16_f32 v205, v206, v207
	v_mul_f32_e32 v0, v217, v203
	v_mul_f32_e32 v216, v216, v203
	v_pk_mul_f32 v[210:211], v[210:211], v[0:1] op_sel_hi:[1,0]
	v_pk_mul_f32 v[212:213], v[212:213], v[216:217] op_sel_hi:[1,0]
	v_pk_mul_f32 v[212:213], v[140:141], v[212:213]
	v_pk_mul_f32 v[210:211], v[138:139], v[210:211]
	v_cvt_pk_bf16_f32 v207, v212, v213
	v_cvt_pk_bf16_f32 v206, v210, v211
	v_lshl_add_u64 v[210:211], v[174:175], 0, v[208:209]
	global_store_dwordx4 v[210:211], v[204:207], off
	v_lshl_add_u64 v[208:209], v[176:177], 0, v[208:209]
	s_nop 0
	v_pk_mul_f32 v[206:207], v[38:39], s[8:9] op_sel_hi:[1,0]
	v_pk_mul_f32 v[204:205], v[40:41], s[8:9] op_sel_hi:[1,0]
	v_min_f32_e32 v0, 0x41e6d4ca, v206
	v_exp_f32_e32 v211, v0
	v_min_f32_e32 v0, 0x41e6d4ca, v207
	v_exp_f32_e32 v210, v0
	v_min_f32_e32 v0, 0x41e6d4ca, v204
	v_exp_f32_e32 v207, v0
	v_min_f32_e32 v0, 0x41e6d4ca, v205
	v_exp_f32_e32 v206, v0
	v_pk_add_f32 v[204:205], v[210:211], 1.0 op_sel_hi:[1,0]
	v_pk_add_f32 v[206:207], v[206:207], 1.0 op_sel_hi:[1,0]
	v_mul_f32_e32 v210, v205, v204
	v_mul_f32_e32 v211, v207, v206
	v_mul_f32_e32 v0, v210, v211
	v_rcp_f32_e32 v203, v0
	s_nop 0
	v_mul_f32_e32 v210, v210, v203
	v_pk_mul_f32 v[206:207], v[206:207], v[210:211] op_sel_hi:[1,0]
	v_mul_f32_e32 v0, v211, v203
	v_pk_mul_f32 v[206:207], v[136:137], v[206:207]
	v_pk_mul_f32 v[212:213], v[34:35], s[8:9] op_sel_hi:[1,0]
	v_pk_mul_f32 v[204:205], v[204:205], v[0:1] op_sel_hi:[1,0]
	v_min_f32_e32 v0, 0x41e6d4ca, v212
	v_pk_mul_f32 v[204:205], v[134:135], v[204:205]
	v_pk_mul_f32 v[210:211], v[36:37], s[8:9] op_sel_hi:[1,0]
	v_exp_f32_e32 v217, v0
	v_min_f32_e32 v0, 0x41e6d4ca, v213
	v_exp_f32_e32 v216, v0
	v_min_f32_e32 v0, 0x41e6d4ca, v210
	v_exp_f32_e32 v213, v0
	v_min_f32_e32 v0, 0x41e6d4ca, v211
	v_exp_f32_e32 v212, v0
	v_pk_add_f32 v[210:211], v[216:217], 1.0 op_sel_hi:[1,0]
	v_cvt_pk_bf16_f32 v204, v204, v205
	v_pk_add_f32 v[212:213], v[212:213], 1.0 op_sel_hi:[1,0]
	v_mul_f32_e32 v216, v211, v210
	v_mul_f32_e32 v217, v213, v212
	v_mul_f32_e32 v0, v216, v217
	v_rcp_f32_e32 v203, v0
	v_cvt_pk_bf16_f32 v205, v206, v207
	v_mul_f32_e32 v0, v217, v203
	v_mul_f32_e32 v216, v216, v203
	v_pk_mul_f32 v[210:211], v[210:211], v[0:1] op_sel_hi:[1,0]
	v_pk_mul_f32 v[212:213], v[212:213], v[216:217] op_sel_hi:[1,0]
	v_pk_mul_f32 v[212:213], v[132:133], v[212:213]
	v_pk_mul_f32 v[210:211], v[130:131], v[210:211]
	v_cvt_pk_bf16_f32 v207, v212, v213
	v_cvt_pk_bf16_f32 v206, v210, v211
	v_add_u32_e32 v0, 0xa0, v202
	global_store_dwordx4 v[208:209], v[204:207], off
	v_ashrrev_i32_e32 v203, 31, v0
	v_mul_lo_u32 v203, s56, v203
	v_pk_mul_f32 v[206:207], v[30:31], s[8:9] op_sel_hi:[1,0]
	v_mul_lo_u32 v204, s57, v0
	v_mad_u64_u32 v[208:209], s[10:11], s56, v0, 0
	v_min_f32_e32 v0, 0x41e6d4ca, v206
	v_add3_u32 v209, v209, v203, v204
	v_pk_mul_f32 v[204:205], v[32:33], s[8:9] op_sel_hi:[1,0]
	v_exp_f32_e32 v211, v0
	v_min_f32_e32 v0, 0x41e6d4ca, v207
	v_exp_f32_e32 v210, v0
	v_min_f32_e32 v0, 0x41e6d4ca, v204
	v_exp_f32_e32 v207, v0
	v_min_f32_e32 v0, 0x41e6d4ca, v205
	v_exp_f32_e32 v206, v0
	v_pk_add_f32 v[204:205], v[210:211], 1.0 op_sel_hi:[1,0]
	v_lshlrev_b64 v[208:209], 1, v[208:209]
	v_pk_add_f32 v[206:207], v[206:207], 1.0 op_sel_hi:[1,0]
	v_mul_f32_e32 v210, v205, v204
	v_mul_f32_e32 v211, v207, v206
	v_mul_f32_e32 v0, v210, v211
	v_rcp_f32_e32 v203, v0
	v_lshl_add_u64 v[176:177], v[176:177], 0, v[208:209]
	v_mul_f32_e32 v210, v210, v203
	v_pk_mul_f32 v[206:207], v[206:207], v[210:211] op_sel_hi:[1,0]
	v_mul_f32_e32 v0, v211, v203
	v_pk_mul_f32 v[206:207], v[144:145], v[206:207]
	v_pk_mul_f32 v[212:213], v[26:27], s[8:9] op_sel_hi:[1,0]
	v_pk_mul_f32 v[204:205], v[204:205], v[0:1] op_sel_hi:[1,0]
	v_min_f32_e32 v0, 0x41e6d4ca, v212
	v_pk_mul_f32 v[204:205], v[142:143], v[204:205]
	v_pk_mul_f32 v[210:211], v[28:29], s[8:9] op_sel_hi:[1,0]
	v_exp_f32_e32 v217, v0
	v_min_f32_e32 v0, 0x41e6d4ca, v213
	v_exp_f32_e32 v216, v0
	v_min_f32_e32 v0, 0x41e6d4ca, v210
	v_exp_f32_e32 v213, v0
	v_min_f32_e32 v0, 0x41e6d4ca, v211
	v_exp_f32_e32 v212, v0
	v_pk_add_f32 v[210:211], v[216:217], 1.0 op_sel_hi:[1,0]
	v_cvt_pk_bf16_f32 v204, v204, v205
	v_pk_add_f32 v[212:213], v[212:213], 1.0 op_sel_hi:[1,0]
	v_mul_f32_e32 v216, v211, v210
	v_mul_f32_e32 v217, v213, v212
	v_mul_f32_e32 v0, v216, v217
	v_rcp_f32_e32 v203, v0
	v_cvt_pk_bf16_f32 v205, v206, v207
	v_mul_f32_e32 v0, v217, v203
	v_mul_f32_e32 v216, v216, v203
	v_pk_mul_f32 v[210:211], v[210:211], v[0:1] op_sel_hi:[1,0]
	v_pk_mul_f32 v[212:213], v[212:213], v[216:217] op_sel_hi:[1,0]
	v_pk_mul_f32 v[212:213], v[140:141], v[212:213]
	v_pk_mul_f32 v[210:211], v[138:139], v[210:211]
	v_cvt_pk_bf16_f32 v207, v212, v213
	v_cvt_pk_bf16_f32 v206, v210, v211
	v_lshl_add_u64 v[210:211], v[174:175], 0, v[208:209]
	global_store_dwordx4 v[210:211], v[204:207], off
	s_nop 1
	v_pk_mul_f32 v[206:207], v[22:23], s[8:9] op_sel_hi:[1,0]
	v_pk_mul_f32 v[204:205], v[24:25], s[8:9] op_sel_hi:[1,0]
	v_min_f32_e32 v0, 0x41e6d4ca, v206
	v_exp_f32_e32 v211, v0
	v_min_f32_e32 v0, 0x41e6d4ca, v207
	v_exp_f32_e32 v210, v0
	v_min_f32_e32 v0, 0x41e6d4ca, v204
	v_exp_f32_e32 v207, v0
	v_min_f32_e32 v0, 0x41e6d4ca, v205
	v_exp_f32_e32 v206, v0
	v_pk_add_f32 v[204:205], v[210:211], 1.0 op_sel_hi:[1,0]
	v_pk_add_f32 v[206:207], v[206:207], 1.0 op_sel_hi:[1,0]
	v_mul_f32_e32 v210, v205, v204
	v_mul_f32_e32 v211, v207, v206
	v_mul_f32_e32 v0, v210, v211
	v_rcp_f32_e32 v203, v0
	s_nop 0
	v_mul_f32_e32 v210, v210, v203
	v_pk_mul_f32 v[206:207], v[206:207], v[210:211] op_sel_hi:[1,0]
	v_mul_f32_e32 v0, v211, v203
	v_pk_mul_f32 v[206:207], v[136:137], v[206:207]
	v_pk_mul_f32 v[212:213], v[18:19], s[8:9] op_sel_hi:[1,0]
	v_pk_mul_f32 v[204:205], v[204:205], v[0:1] op_sel_hi:[1,0]
	v_min_f32_e32 v0, 0x41e6d4ca, v212
	v_pk_mul_f32 v[204:205], v[134:135], v[204:205]
	v_pk_mul_f32 v[210:211], v[20:21], s[8:9] op_sel_hi:[1,0]
	v_exp_f32_e32 v217, v0
	v_min_f32_e32 v0, 0x41e6d4ca, v213
	v_exp_f32_e32 v216, v0
	v_min_f32_e32 v0, 0x41e6d4ca, v210
	v_exp_f32_e32 v213, v0
	v_min_f32_e32 v0, 0x41e6d4ca, v211
	v_exp_f32_e32 v212, v0
	v_pk_add_f32 v[210:211], v[216:217], 1.0 op_sel_hi:[1,0]
	v_cvt_pk_bf16_f32 v204, v204, v205
	v_pk_add_f32 v[212:213], v[212:213], 1.0 op_sel_hi:[1,0]
	v_mul_f32_e32 v216, v211, v210
	v_mul_f32_e32 v217, v213, v212
	v_mul_f32_e32 v0, v216, v217
	v_rcp_f32_e32 v203, v0
	v_cvt_pk_bf16_f32 v205, v206, v207
	v_mul_f32_e32 v0, v217, v203
	v_mul_f32_e32 v216, v216, v203
	v_pk_mul_f32 v[210:211], v[210:211], v[0:1] op_sel_hi:[1,0]
	v_pk_mul_f32 v[212:213], v[212:213], v[216:217] op_sel_hi:[1,0]
	v_pk_mul_f32 v[212:213], v[132:133], v[212:213]
	v_pk_mul_f32 v[210:211], v[130:131], v[210:211]
	v_cvt_pk_bf16_f32 v207, v212, v213
	v_cvt_pk_bf16_f32 v206, v210, v211
	v_add_u32_e32 v0, 0xb0, v202
	global_store_dwordx4 v[176:177], v[204:207], off
	v_ashrrev_i32_e32 v176, 31, v0
	v_mul_lo_u32 v203, s56, v176
	v_pk_mul_f32 v[206:207], v[14:15], s[8:9] op_sel_hi:[1,0]
	v_mul_lo_u32 v204, s57, v0
	v_mad_u64_u32 v[176:177], s[10:11], s56, v0, 0
	v_min_f32_e32 v0, 0x41e6d4ca, v206
	v_add3_u32 v177, v177, v203, v204
	v_pk_mul_f32 v[204:205], v[16:17], s[8:9] op_sel_hi:[1,0]
	v_exp_f32_e32 v209, v0
	v_min_f32_e32 v0, 0x41e6d4ca, v207
	v_exp_f32_e32 v208, v0
	v_min_f32_e32 v0, 0x41e6d4ca, v204
	v_exp_f32_e32 v207, v0
	v_min_f32_e32 v0, 0x41e6d4ca, v205
	v_exp_f32_e32 v206, v0
	v_pk_add_f32 v[204:205], v[208:209], 1.0 op_sel_hi:[1,0]
	v_pk_add_f32 v[206:207], v[206:207], 1.0 op_sel_hi:[1,0]
	v_mul_f32_e32 v208, v205, v204
	v_mul_f32_e32 v209, v207, v206
	v_mul_f32_e32 v0, v208, v209
	v_rcp_f32_e32 v203, v0
	s_nop 0
	v_mul_f32_e32 v208, v208, v203
	v_pk_mul_f32 v[206:207], v[206:207], v[208:209] op_sel_hi:[1,0]
	v_mul_f32_e32 v0, v209, v203
	v_pk_mul_f32 v[144:145], v[144:145], v[206:207]
	v_pk_mul_f32 v[206:207], v[10:11], s[8:9] op_sel_hi:[1,0]
	v_pk_mul_f32 v[204:205], v[204:205], v[0:1] op_sel_hi:[1,0]
	v_min_f32_e32 v0, 0x41e6d4ca, v206
	v_pk_mul_f32 v[142:143], v[142:143], v[204:205]
	v_pk_mul_f32 v[204:205], v[12:13], s[8:9] op_sel_hi:[1,0]
	v_exp_f32_e32 v209, v0
	v_min_f32_e32 v0, 0x41e6d4ca, v207
	v_exp_f32_e32 v208, v0
	v_min_f32_e32 v0, 0x41e6d4ca, v204
	v_exp_f32_e32 v207, v0
	v_min_f32_e32 v0, 0x41e6d4ca, v205
	v_exp_f32_e32 v206, v0
	v_pk_add_f32 v[204:205], v[208:209], 1.0 op_sel_hi:[1,0]
	s_nop 0
	v_mov_b32_e32 v208, v205
	v_pk_add_f32 v[206:207], v[206:207], 1.0 op_sel_hi:[1,0]
	v_mov_b32_e32 v210, v204
	v_mov_b32_e32 v209, v207
	v_mov_b32_e32 v211, v206
	v_pk_mul_f32 v[208:209], v[208:209], v[210:211]
	s_nop 0
	v_mul_f32_e32 v0, v208, v209
	v_rcp_f32_e32 v203, v0
	s_mov_b64 s[10:11], 0
	v_mul_f32_e32 v0, v209, v203
	v_mul_f32_e32 v208, v208, v203
	v_pk_mul_f32 v[204:205], v[204:205], v[0:1] op_sel_hi:[1,0]
	v_pk_mul_f32 v[206:207], v[206:207], v[208:209] op_sel_hi:[1,0]
	s_nop 0
	v_pk_mul_f32 v[206:207], v[140:141], v[206:207]
	v_pk_mul_f32 v[140:141], v[138:139], v[204:205]
	v_cvt_pk_bf16_f32 v138, v142, v143
	v_cvt_pk_bf16_f32 v139, v144, v145
	v_cvt_pk_bf16_f32 v140, v140, v141
	v_cvt_pk_bf16_f32 v141, v206, v207
	v_lshl_add_u64 v[142:143], v[176:177], 1, v[174:175]
	global_store_dwordx4 v[142:143], v[138:141], off
	s_nop 1
	v_pk_mul_f32 v[140:141], v[6:7], s[8:9] op_sel_hi:[1,0]
	v_pk_mul_f32 v[138:139], v[8:9], s[8:9] op_sel_hi:[1,0]
	v_min_f32_e32 v0, 0x41e6d4ca, v140
	v_exp_f32_e32 v143, v0
	v_min_f32_e32 v0, 0x41e6d4ca, v141
	v_exp_f32_e32 v142, v0
	v_min_f32_e32 v0, 0x41e6d4ca, v138
	v_exp_f32_e32 v141, v0
	v_min_f32_e32 v0, 0x41e6d4ca, v139
	v_exp_f32_e32 v140, v0
	v_pk_add_f32 v[138:139], v[142:143], 1.0 op_sel_hi:[1,0]
	v_pk_add_f32 v[140:141], v[140:141], 1.0 op_sel_hi:[1,0]
	v_mul_f32_e32 v142, v139, v138
	v_mul_f32_e32 v143, v141, v140
	s_nop 0
	v_mul_f32_e32 v0, v142, v143
	v_rcp_f32_e32 v144, v0
	s_nop 0
	v_mul_f32_e32 v0, v143, v144
	v_pk_mul_f32 v[138:139], v[138:139], v[0:1] op_sel_hi:[1,0]
	v_mul_f32_e32 v142, v142, v144
	v_pk_mul_f32 v[134:135], v[134:135], v[138:139]
	v_pk_mul_f32 v[138:139], v[2:3], s[8:9] op_sel_hi:[1,0]
	v_pk_mul_f32 v[140:141], v[140:141], v[142:143] op_sel_hi:[1,0]
	v_min_f32_e32 v0, 0x41e6d4ca, v138
	v_pk_mul_f32 v[140:141], v[136:137], v[140:141]
	v_pk_mul_f32 v[136:137], v[4:5], s[8:9] op_sel_hi:[1,0]
	v_exp_f32_e32 v143, v0
	v_min_f32_e32 v0, 0x41e6d4ca, v139
	v_exp_f32_e32 v142, v0
	v_min_f32_e32 v0, 0x41e6d4ca, v136
	v_exp_f32_e32 v139, v0
	v_min_f32_e32 v0, 0x41e6d4ca, v137
	v_exp_f32_e32 v138, v0
	v_pk_add_f32 v[136:137], v[142:143], 1.0 op_sel_hi:[1,0]
	v_pk_add_f32 v[138:139], v[138:139], 1.0 op_sel_hi:[1,0]
	v_mul_f32_e32 v142, v137, v136
	v_mul_f32_e32 v143, v139, v138
	s_nop 0
	v_mul_f32_e32 v0, v142, v143
	v_rcp_f32_e32 v144, v0
	s_nop 0
	v_mul_f32_e32 v0, v143, v144
	v_mul_f32_e32 v142, v142, v144
	v_pk_mul_f32 v[144:145], v[136:137], v[0:1] op_sel_hi:[1,0]
	v_pk_mul_f32 v[136:137], v[138:139], v[142:143] op_sel_hi:[1,0]
	s_nop 0
	v_pk_mul_f32 v[136:137], v[132:133], v[136:137]
	v_pk_mul_f32 v[132:133], v[130:131], v[144:145]
	v_cvt_pk_bf16_f32 v130, v134, v135
	v_cvt_pk_bf16_f32 v131, v140, v141
	v_cvt_pk_bf16_f32 v132, v132, v133
	s_branch .LBB0_205
.Lsig_m1:
	v_ashrrev_i32_e32 v0, 31, v202
	v_mul_lo_u32 v174, s57, v202
	v_mul_lo_u32 v0, s56, v0
	v_mad_u64_u32 v[176:177], s[10:11], s56, v202, 0
	v_add3_u32 v177, v177, v0, v174
	v_pk_mul_f32 v[174:175], v[128:129], s[8:9] op_sel_hi:[1,0]
	v_pk_mul_f32 v[204:205], v[126:127], s[8:9] op_sel_hi:[1,0]
	v_min_f32_e32 v174, 0x41e6d4ca, v174
	v_min_f32_e32 v203, 0x41e6d4ca, v204
	v_exp_f32_e32 v207, v203
	v_min_f32_e32 v203, 0x41e6d4ca, v205
	v_exp_f32_e32 v205, v174
	v_min_f32_e32 v174, 0x41e6d4ca, v175
	v_exp_f32_e32 v206, v203
	v_exp_f32_e32 v204, v174
	v_pk_add_f32 v[174:175], v[206:207], 1.0 op_sel_hi:[1,0]
	v_pk_add_f32 v[204:205], v[204:205], 1.0 op_sel_hi:[1,0]
	v_mul_f32_e32 v206, v175, v174
	v_mul_f32_e32 v207, v205, v204
	s_nop 0
	v_mul_f32_e32 v203, v206, v207
	v_rcp_f32_e32 v203, v203
	s_nop 0
	v_mul_f32_e32 v208, v207, v203
	v_mul_f32_e32 v206, v206, v203
	v_pk_mul_f32 v[174:175], v[174:175], v[208:209] op_sel_hi:[1,0]
	v_pk_mul_f32 v[204:205], v[204:205], v[206:207] op_sel_hi:[1,0]
	s_waitcnt vmcnt(0)
	v_pk_mul_f32 v[174:175], v[126:127], v[174:175]
	v_pk_mul_f32 v[206:207], v[122:123], s[8:9] op_sel_hi:[1,0]
	s_nop 0
	v_min_f32_e32 v203, 0x41e6d4ca, v206
	v_pk_mul_f32 v[208:209], v[128:129], v[204:205]
	v_pk_mul_f32 v[204:205], v[124:125], s[8:9] op_sel_hi:[1,0]
	v_exp_f32_e32 v211, v203
	v_min_f32_e32 v203, 0x41e6d4ca, v207
	v_exp_f32_e32 v210, v203
	v_min_f32_e32 v203, 0x41e6d4ca, v204
	v_exp_f32_e32 v207, v203
	v_min_f32_e32 v203, 0x41e6d4ca, v205
	v_exp_f32_e32 v206, v203
	v_pk_add_f32 v[204:205], v[210:211], 1.0 op_sel_hi:[1,0]
	v_pk_add_f32 v[206:207], v[206:207], 1.0 op_sel_hi:[1,0]
	v_mul_f32_e32 v210, v205, v204
	v_mul_f32_e32 v211, v207, v206
	s_nop 0
	v_mul_f32_e32 v203, v210, v211
	v_rcp_f32_e32 v203, v203
	s_nop 0
	v_mul_f32_e32 v212, v211, v203
	v_mul_f32_e32 v210, v210, v203
	v_pk_mul_f32 v[204:205], v[204:205], v[212:213] op_sel_hi:[1,0]
	v_pk_mul_f32 v[206:207], v[206:207], v[210:211] op_sel_hi:[1,0]
	v_pk_mul_f32 v[212:213], v[124:125], v[206:207]
	v_pk_mul_f32 v[206:207], v[122:123], v[204:205]
	v_cvt_pk_bf16_f32 v204, v174, v175
	v_cvt_pk_bf16_f32 v205, v208, v209
	v_lshl_add_u64 v[174:175], v[170:171], 1, s[86:87]
	v_lshlrev_b64 v[208:209], 1, v[176:177]
	v_cvt_pk_bf16_f32 v206, v206, v207
	v_cvt_pk_bf16_f32 v207, v212, v213
	v_lshl_add_u64 v[176:177], v[174:175], 0, v[208:209]
	global_store_dwordx4 v[176:177], v[204:207], off
	v_pk_mul_f32 v[176:177], v[120:121], s[8:9] op_sel_hi:[1,0]
	s_nop 0
	v_pk_mul_f32 v[204:205], v[118:119], s[8:9] op_sel_hi:[1,0]
	v_min_f32_e32 v176, 0x41e6d4ca, v176
	v_min_f32_e32 v203, 0x41e6d4ca, v204
	v_exp_f32_e32 v207, v203
	v_min_f32_e32 v203, 0x41e6d4ca, v205
	v_exp_f32_e32 v205, v176
	v_min_f32_e32 v176, 0x41e6d4ca, v177
	v_exp_f32_e32 v206, v203
	v_exp_f32_e32 v204, v176
	v_pk_add_f32 v[176:177], v[206:207], 1.0 op_sel_hi:[1,0]
	v_pk_add_f32 v[204:205], v[204:205], 1.0 op_sel_hi:[1,0]
	v_mul_f32_e32 v206, v177, v176
	v_mul_f32_e32 v207, v205, v204
	s_nop 0
	v_mul_f32_e32 v203, v206, v207
	v_rcp_f32_e32 v203, v203
	s_nop 0
	v_mul_f32_e32 v210, v207, v203
	v_mul_f32_e32 v206, v206, v203
	v_pk_mul_f32 v[176:177], v[176:177], v[210:211] op_sel_hi:[1,0]
	v_pk_mul_f32 v[204:205], v[204:205], v[206:207] op_sel_hi:[1,0]
	v_pk_mul_f32 v[176:177], v[118:119], v[176:177]
	v_pk_mul_f32 v[206:207], v[114:115], s[8:9] op_sel_hi:[1,0]
	s_nop 0
	v_min_f32_e32 v203, 0x41e6d4ca, v206
	v_pk_mul_f32 v[210:211], v[120:121], v[204:205]
	v_pk_mul_f32 v[204:205], v[116:117], s[8:9] op_sel_hi:[1,0]
	v_exp_f32_e32 v213, v203
	v_min_f32_e32 v203, 0x41e6d4ca, v207
	v_exp_f32_e32 v212, v203
	v_min_f32_e32 v203, 0x41e6d4ca, v204
	v_exp_f32_e32 v207, v203
	v_min_f32_e32 v203, 0x41e6d4ca, v205
	v_exp_f32_e32 v206, v203
	v_pk_add_f32 v[204:205], v[212:213], 1.0 op_sel_hi:[1,0]
	v_pk_add_f32 v[206:207], v[206:207], 1.0 op_sel_hi:[1,0]
	v_mul_f32_e32 v212, v205, v204
	v_mul_f32_e32 v213, v207, v206
	s_nop 0
	v_mul_f32_e32 v203, v212, v213
	v_rcp_f32_e32 v203, v203
	s_nop 0
	v_mul_f32_e32 v216, v213, v203
	v_mul_f32_e32 v212, v212, v203
	v_pk_mul_f32 v[204:205], v[204:205], v[216:217] op_sel_hi:[1,0]
	v_pk_mul_f32 v[206:207], v[206:207], v[212:213] op_sel_hi:[1,0]
	v_pk_mul_f32 v[216:217], v[116:117], v[206:207]
	v_pk_mul_f32 v[206:207], v[114:115], v[204:205]
	v_cvt_pk_bf16_f32 v204, v176, v177
	v_lshl_add_u64 v[176:177], v[172:173], 1, s[86:87]
	v_cvt_pk_bf16_f32 v205, v210, v211
	v_cvt_pk_bf16_f32 v206, v206, v207
	v_cvt_pk_bf16_f32 v207, v216, v217
	v_lshl_add_u64 v[208:209], v[176:177], 0, v[208:209]
	global_store_dwordx4 v[208:209], v[204:207], off
	v_or_b32_e32 v203, 16, v202
	v_mad_u64_u32 v[208:209], s[10:11], s56, v203, 0
	v_pk_mul_f32 v[206:207], v[110:111], s[8:9] op_sel_hi:[1,0]
	v_mul_lo_u32 v204, s57, v203
	v_min_f32_e32 v203, 0x41e6d4ca, v206
	v_add3_u32 v209, v209, v0, v204
	v_pk_mul_f32 v[204:205], v[112:113], s[8:9] op_sel_hi:[1,0]
	v_exp_f32_e32 v211, v203
	v_min_f32_e32 v203, 0x41e6d4ca, v207
	v_exp_f32_e32 v210, v203
	v_min_f32_e32 v203, 0x41e6d4ca, v204
	v_exp_f32_e32 v207, v203
	v_min_f32_e32 v203, 0x41e6d4ca, v205
	v_exp_f32_e32 v206, v203
	v_pk_add_f32 v[204:205], v[210:211], 1.0 op_sel_hi:[1,0]
	v_lshlrev_b64 v[208:209], 1, v[208:209]
	v_pk_add_f32 v[206:207], v[206:207], 1.0 op_sel_hi:[1,0]
	v_mul_f32_e32 v210, v205, v204
	v_mul_f32_e32 v211, v207, v206
	s_nop 0
	v_mul_f32_e32 v203, v210, v211
	v_rcp_f32_e32 v203, v203
	s_nop 0
	v_mul_f32_e32 v212, v211, v203
	v_mul_f32_e32 v210, v210, v203
	v_pk_mul_f32 v[204:205], v[204:205], v[212:213] op_sel_hi:[1,0]
	v_pk_mul_f32 v[206:207], v[206:207], v[210:211] op_sel_hi:[1,0]
	v_pk_mul_f32 v[206:207], v[112:113], v[206:207]
	v_pk_mul_f32 v[212:213], v[106:107], s[8:9] op_sel_hi:[1,0]
	s_nop 0
	v_min_f32_e32 v203, 0x41e6d4ca, v212
	v_pk_mul_f32 v[204:205], v[110:111], v[204:205]
	v_pk_mul_f32 v[210:211], v[108:109], s[8:9] op_sel_hi:[1,0]
	v_exp_f32_e32 v217, v203
	v_min_f32_e32 v203, 0x41e6d4ca, v213
	v_exp_f32_e32 v216, v203
	v_min_f32_e32 v203, 0x41e6d4ca, v210
	v_exp_f32_e32 v213, v203
	v_min_f32_e32 v203, 0x41e6d4ca, v211
	v_exp_f32_e32 v212, v203
	v_pk_add_f32 v[210:211], v[216:217], 1.0 op_sel_hi:[1,0]
	v_cvt_pk_bf16_f32 v204, v204, v205
	v_pk_add_f32 v[212:213], v[212:213], 1.0 op_sel_hi:[1,0]
	v_mul_f32_e32 v216, v211, v210
	v_mul_f32_e32 v217, v213, v212
	v_cvt_pk_bf16_f32 v205, v206, v207
	v_mul_f32_e32 v203, v216, v217
	v_rcp_f32_e32 v203, v203
	s_nop 0
	v_mul_f32_e32 v218, v217, v203
	v_mul_f32_e32 v216, v216, v203
	v_pk_mul_f32 v[210:211], v[210:211], v[218:219] op_sel_hi:[1,0]
	v_pk_mul_f32 v[212:213], v[212:213], v[216:217] op_sel_hi:[1,0]
	v_pk_mul_f32 v[212:213], v[108:109], v[212:213]
	v_pk_mul_f32 v[210:211], v[106:107], v[210:211]
	v_cvt_pk_bf16_f32 v207, v212, v213
	v_cvt_pk_bf16_f32 v206, v210, v211
	v_lshl_add_u64 v[210:211], v[174:175], 0, v[208:209]
	global_store_dwordx4 v[210:211], v[204:207], off
	v_lshl_add_u64 v[208:209], v[176:177], 0, v[208:209]
	s_nop 0
	v_pk_mul_f32 v[206:207], v[102:103], s[8:9] op_sel_hi:[1,0]
	v_pk_mul_f32 v[204:205], v[104:105], s[8:9] op_sel_hi:[1,0]
	v_min_f32_e32 v203, 0x41e6d4ca, v206
	v_exp_f32_e32 v211, v203
	v_min_f32_e32 v203, 0x41e6d4ca, v207
	v_exp_f32_e32 v210, v203
	v_min_f32_e32 v203, 0x41e6d4ca, v204
	v_exp_f32_e32 v207, v203
	v_min_f32_e32 v203, 0x41e6d4ca, v205
	v_exp_f32_e32 v206, v203
	v_pk_add_f32 v[204:205], v[210:211], 1.0 op_sel_hi:[1,0]
	v_pk_add_f32 v[206:207], v[206:207], 1.0 op_sel_hi:[1,0]
	v_mul_f32_e32 v210, v205, v204
	v_mul_f32_e32 v211, v207, v206
	s_nop 0
	v_mul_f32_e32 v203, v210, v211
	v_rcp_f32_e32 v203, v203
	s_nop 0
	v_mul_f32_e32 v212, v211, v203
	v_mul_f32_e32 v210, v210, v203
	v_pk_mul_f32 v[204:205], v[204:205], v[212:213] op_sel_hi:[1,0]
	v_pk_mul_f32 v[206:207], v[206:207], v[210:211] op_sel_hi:[1,0]
	v_pk_mul_f32 v[206:207], v[104:105], v[206:207]
	v_pk_mul_f32 v[212:213], v[98:99], s[8:9] op_sel_hi:[1,0]
	s_nop 0
	v_min_f32_e32 v203, 0x41e6d4ca, v212
	v_pk_mul_f32 v[204:205], v[102:103], v[204:205]
	v_pk_mul_f32 v[210:211], v[100:101], s[8:9] op_sel_hi:[1,0]
	v_exp_f32_e32 v217, v203
	v_min_f32_e32 v203, 0x41e6d4ca, v213
	v_exp_f32_e32 v216, v203
	v_min_f32_e32 v203, 0x41e6d4ca, v210
	v_exp_f32_e32 v213, v203
	v_min_f32_e32 v203, 0x41e6d4ca, v211
	v_exp_f32_e32 v212, v203
	v_pk_add_f32 v[210:211], v[216:217], 1.0 op_sel_hi:[1,0]
	v_cvt_pk_bf16_f32 v204, v204, v205
	v_pk_add_f32 v[212:213], v[212:213], 1.0 op_sel_hi:[1,0]
	v_mul_f32_e32 v216, v211, v210
	v_mul_f32_e32 v217, v213, v212
	v_cvt_pk_bf16_f32 v205, v206, v207
	v_mul_f32_e32 v203, v216, v217
	v_rcp_f32_e32 v203, v203
	s_nop 0
	v_mul_f32_e32 v218, v217, v203
	v_mul_f32_e32 v216, v216, v203
	v_pk_mul_f32 v[210:211], v[210:211], v[218:219] op_sel_hi:[1,0]
	v_pk_mul_f32 v[212:213], v[212:213], v[216:217] op_sel_hi:[1,0]
	v_pk_mul_f32 v[212:213], v[100:101], v[212:213]
	v_pk_mul_f32 v[210:211], v[98:99], v[210:211]
	v_cvt_pk_bf16_f32 v207, v212, v213
	v_cvt_pk_bf16_f32 v206, v210, v211
	global_store_dwordx4 v[208:209], v[204:207], off
	v_or_b32_e32 v203, 32, v202
	v_mad_u64_u32 v[208:209], s[10:11], s56, v203, 0
	v_pk_mul_f32 v[206:207], v[94:95], s[8:9] op_sel_hi:[1,0]
	v_mul_lo_u32 v204, s57, v203
	v_min_f32_e32 v203, 0x41e6d4ca, v206
	v_add3_u32 v209, v209, v0, v204
	v_pk_mul_f32 v[204:205], v[96:97], s[8:9] op_sel_hi:[1,0]
	v_exp_f32_e32 v211, v203
	v_min_f32_e32 v203, 0x41e6d4ca, v207
	v_exp_f32_e32 v210, v203
	v_min_f32_e32 v203, 0x41e6d4ca, v204
	v_exp_f32_e32 v207, v203
	v_min_f32_e32 v203, 0x41e6d4ca, v205
	v_exp_f32_e32 v206, v203
	v_pk_add_f32 v[204:205], v[210:211], 1.0 op_sel_hi:[1,0]
	v_lshlrev_b64 v[208:209], 1, v[208:209]
	v_pk_add_f32 v[206:207], v[206:207], 1.0 op_sel_hi:[1,0]
	v_mul_f32_e32 v210, v205, v204
	v_mul_f32_e32 v211, v207, v206
	s_nop 0
	v_mul_f32_e32 v203, v210, v211
	v_rcp_f32_e32 v203, v203
	s_nop 0
	v_mul_f32_e32 v212, v211, v203
	v_mul_f32_e32 v210, v210, v203
	v_pk_mul_f32 v[204:205], v[204:205], v[212:213] op_sel_hi:[1,0]
	v_pk_mul_f32 v[206:207], v[206:207], v[210:211] op_sel_hi:[1,0]
	v_pk_mul_f32 v[206:207], v[96:97], v[206:207]
	v_pk_mul_f32 v[212:213], v[90:91], s[8:9] op_sel_hi:[1,0]
	s_nop 0
	v_min_f32_e32 v203, 0x41e6d4ca, v212
	v_pk_mul_f32 v[204:205], v[94:95], v[204:205]
	v_pk_mul_f32 v[210:211], v[92:93], s[8:9] op_sel_hi:[1,0]
	v_exp_f32_e32 v217, v203
	v_min_f32_e32 v203, 0x41e6d4ca, v213
	v_exp_f32_e32 v216, v203
	v_min_f32_e32 v203, 0x41e6d4ca, v210
	v_exp_f32_e32 v213, v203
	v_min_f32_e32 v203, 0x41e6d4ca, v211
	v_exp_f32_e32 v212, v203
	v_pk_add_f32 v[210:211], v[216:217], 1.0 op_sel_hi:[1,0]
	v_cvt_pk_bf16_f32 v204, v204, v205
	v_pk_add_f32 v[212:213], v[212:213], 1.0 op_sel_hi:[1,0]
	v_mul_f32_e32 v216, v211, v210
	v_mul_f32_e32 v217, v213, v212
	v_cvt_pk_bf16_f32 v205, v206, v207
	v_mul_f32_e32 v203, v216, v217
	v_rcp_f32_e32 v203, v203
	s_nop 0
	v_mul_f32_e32 v218, v217, v203
	v_mul_f32_e32 v216, v216, v203
	v_pk_mul_f32 v[210:211], v[210:211], v[218:219] op_sel_hi:[1,0]
	v_pk_mul_f32 v[212:213], v[212:213], v[216:217] op_sel_hi:[1,0]
	v_pk_mul_f32 v[212:213], v[92:93], v[212:213]
	v_pk_mul_f32 v[210:211], v[90:91], v[210:211]
	v_cvt_pk_bf16_f32 v207, v212, v213
	v_cvt_pk_bf16_f32 v206, v210, v211
	v_lshl_add_u64 v[210:211], v[174:175], 0, v[208:209]
	global_store_dwordx4 v[210:211], v[204:207], off
	v_lshl_add_u64 v[208:209], v[176:177], 0, v[208:209]
	s_nop 0
	v_pk_mul_f32 v[206:207], v[86:87], s[8:9] op_sel_hi:[1,0]
	v_pk_mul_f32 v[204:205], v[88:89], s[8:9] op_sel_hi:[1,0]
	v_min_f32_e32 v203, 0x41e6d4ca, v206
	v_exp_f32_e32 v211, v203
	v_min_f32_e32 v203, 0x41e6d4ca, v207
	v_exp_f32_e32 v210, v203
	v_min_f32_e32 v203, 0x41e6d4ca, v204
	v_exp_f32_e32 v207, v203
	v_min_f32_e32 v203, 0x41e6d4ca, v205
	v_exp_f32_e32 v206, v203
	v_pk_add_f32 v[204:205], v[210:211], 1.0 op_sel_hi:[1,0]
	v_pk_add_f32 v[206:207], v[206:207], 1.0 op_sel_hi:[1,0]
	v_mul_f32_e32 v210, v205, v204
	v_mul_f32_e32 v211, v207, v206
	s_nop 0
	v_mul_f32_e32 v203, v210, v211
	v_rcp_f32_e32 v203, v203
	s_nop 0
	v_mul_f32_e32 v212, v211, v203
	v_mul_f32_e32 v210, v210, v203
	v_pk_mul_f32 v[204:205], v[204:205], v[212:213] op_sel_hi:[1,0]
	v_pk_mul_f32 v[206:207], v[206:207], v[210:211] op_sel_hi:[1,0]
	v_pk_mul_f32 v[206:207], v[88:89], v[206:207]
	v_pk_mul_f32 v[212:213], v[82:83], s[8:9] op_sel_hi:[1,0]
	s_nop 0
	v_min_f32_e32 v203, 0x41e6d4ca, v212
	v_pk_mul_f32 v[204:205], v[86:87], v[204:205]
	v_pk_mul_f32 v[210:211], v[84:85], s[8:9] op_sel_hi:[1,0]
	v_exp_f32_e32 v217, v203
	v_min_f32_e32 v203, 0x41e6d4ca, v213
	v_exp_f32_e32 v216, v203
	v_min_f32_e32 v203, 0x41e6d4ca, v210
	v_exp_f32_e32 v213, v203
	v_min_f32_e32 v203, 0x41e6d4ca, v211
	v_exp_f32_e32 v212, v203
	v_pk_add_f32 v[210:211], v[216:217], 1.0 op_sel_hi:[1,0]
	v_cvt_pk_bf16_f32 v204, v204, v205
	v_pk_add_f32 v[212:213], v[212:213], 1.0 op_sel_hi:[1,0]
	v_mul_f32_e32 v216, v211, v210
	v_mul_f32_e32 v217, v213, v212
	v_cvt_pk_bf16_f32 v205, v206, v207
	v_mul_f32_e32 v203, v216, v217
	v_rcp_f32_e32 v203, v203
	s_nop 0
	v_mul_f32_e32 v218, v217, v203
	v_mul_f32_e32 v216, v216, v203
	v_pk_mul_f32 v[210:211], v[210:211], v[218:219] op_sel_hi:[1,0]
	v_pk_mul_f32 v[212:213], v[212:213], v[216:217] op_sel_hi:[1,0]
	v_pk_mul_f32 v[212:213], v[84:85], v[212:213]
	v_pk_mul_f32 v[210:211], v[82:83], v[210:211]
	v_cvt_pk_bf16_f32 v207, v212, v213
	v_cvt_pk_bf16_f32 v206, v210, v211
	v_or_b32_e32 v203, 48, v202
	global_store_dwordx4 v[208:209], v[204:207], off
	v_mad_u64_u32 v[208:209], s[10:11], s56, v203, 0
	s_nop 0
	v_mul_lo_u32 v204, s57, v203
	v_pk_mul_f32 v[206:207], v[78:79], s[8:9] op_sel_hi:[1,0]
	v_add3_u32 v209, v209, v0, v204
	v_min_f32_e32 v0, 0x41e6d4ca, v206
	v_pk_mul_f32 v[204:205], v[80:81], s[8:9] op_sel_hi:[1,0]
	v_exp_f32_e32 v211, v0
	v_min_f32_e32 v0, 0x41e6d4ca, v207
	v_exp_f32_e32 v210, v0
	v_min_f32_e32 v0, 0x41e6d4ca, v204
	v_exp_f32_e32 v207, v0
	v_min_f32_e32 v0, 0x41e6d4ca, v205
	v_exp_f32_e32 v206, v0
	v_pk_add_f32 v[204:205], v[210:211], 1.0 op_sel_hi:[1,0]
	v_lshlrev_b64 v[208:209], 1, v[208:209]
	v_pk_add_f32 v[206:207], v[206:207], 1.0 op_sel_hi:[1,0]
	v_mul_f32_e32 v210, v205, v204
	v_mul_f32_e32 v211, v207, v206
	v_mul_f32_e32 v0, v210, v211
	v_rcp_f32_e32 v203, v0
	s_nop 0
	v_mul_f32_e32 v210, v210, v203
	v_pk_mul_f32 v[206:207], v[206:207], v[210:211] op_sel_hi:[1,0]
	v_mul_f32_e32 v0, v211, v203
	v_pk_mul_f32 v[206:207], v[80:81], v[206:207]
	v_pk_mul_f32 v[212:213], v[74:75], s[8:9] op_sel_hi:[1,0]
	v_pk_mul_f32 v[204:205], v[204:205], v[0:1] op_sel_hi:[1,0]
	v_min_f32_e32 v0, 0x41e6d4ca, v212
	v_pk_mul_f32 v[204:205], v[78:79], v[204:205]
	v_pk_mul_f32 v[210:211], v[76:77], s[8:9] op_sel_hi:[1,0]
	v_exp_f32_e32 v217, v0
	v_min_f32_e32 v0, 0x41e6d4ca, v213
	v_exp_f32_e32 v216, v0
	v_min_f32_e32 v0, 0x41e6d4ca, v210
	v_exp_f32_e32 v213, v0
	v_min_f32_e32 v0, 0x41e6d4ca, v211
	v_exp_f32_e32 v212, v0
	v_pk_add_f32 v[210:211], v[216:217], 1.0 op_sel_hi:[1,0]
	v_cvt_pk_bf16_f32 v204, v204, v205
	v_pk_add_f32 v[212:213], v[212:213], 1.0 op_sel_hi:[1,0]
	v_mul_f32_e32 v216, v211, v210
	v_mul_f32_e32 v217, v213, v212
	v_mul_f32_e32 v0, v216, v217
	v_rcp_f32_e32 v203, v0
	v_cvt_pk_bf16_f32 v205, v206, v207
	v_mul_f32_e32 v0, v217, v203
	v_mul_f32_e32 v216, v216, v203
	v_pk_mul_f32 v[210:211], v[210:211], v[0:1] op_sel_hi:[1,0]
	v_pk_mul_f32 v[212:213], v[212:213], v[216:217] op_sel_hi:[1,0]
	v_pk_mul_f32 v[212:213], v[76:77], v[212:213]
	v_pk_mul_f32 v[210:211], v[74:75], v[210:211]
	v_cvt_pk_bf16_f32 v207, v212, v213
	v_cvt_pk_bf16_f32 v206, v210, v211
	v_lshl_add_u64 v[210:211], v[174:175], 0, v[208:209]
	global_store_dwordx4 v[210:211], v[204:207], off
	v_lshl_add_u64 v[208:209], v[176:177], 0, v[208:209]
	s_nop 0
	v_pk_mul_f32 v[206:207], v[70:71], s[8:9] op_sel_hi:[1,0]
	v_pk_mul_f32 v[204:205], v[72:73], s[8:9] op_sel_hi:[1,0]
	v_min_f32_e32 v0, 0x41e6d4ca, v206
	v_exp_f32_e32 v211, v0
	v_min_f32_e32 v0, 0x41e6d4ca, v207
	v_exp_f32_e32 v210, v0
	v_min_f32_e32 v0, 0x41e6d4ca, v204
	v_exp_f32_e32 v207, v0
	v_min_f32_e32 v0, 0x41e6d4ca, v205
	v_exp_f32_e32 v206, v0
	v_pk_add_f32 v[204:205], v[210:211], 1.0 op_sel_hi:[1,0]
	v_pk_add_f32 v[206:207], v[206:207], 1.0 op_sel_hi:[1,0]
	v_mul_f32_e32 v210, v205, v204
	v_mul_f32_e32 v211, v207, v206
	v_mul_f32_e32 v0, v210, v211
	v_rcp_f32_e32 v203, v0
	s_nop 0
	v_mul_f32_e32 v210, v210, v203
	v_pk_mul_f32 v[206:207], v[206:207], v[210:211] op_sel_hi:[1,0]
	v_mul_f32_e32 v0, v211, v203
	v_pk_mul_f32 v[206:207], v[72:73], v[206:207]
	v_pk_mul_f32 v[212:213], v[66:67], s[8:9] op_sel_hi:[1,0]
	v_pk_mul_f32 v[204:205], v[204:205], v[0:1] op_sel_hi:[1,0]
	v_min_f32_e32 v0, 0x41e6d4ca, v212
	v_pk_mul_f32 v[204:205], v[70:71], v[204:205]
	v_pk_mul_f32 v[210:211], v[68:69], s[8:9] op_sel_hi:[1,0]
	v_exp_f32_e32 v217, v0
	v_min_f32_e32 v0, 0x41e6d4ca, v213
	v_exp_f32_e32 v216, v0
	v_min_f32_e32 v0, 0x41e6d4ca, v210
	v_exp_f32_e32 v213, v0
	v_min_f32_e32 v0, 0x41e6d4ca, v211
	v_exp_f32_e32 v212, v0
	v_pk_add_f32 v[210:211], v[216:217], 1.0 op_sel_hi:[1,0]
	v_cvt_pk_bf16_f32 v204, v204, v205
	v_pk_add_f32 v[212:213], v[212:213], 1.0 op_sel_hi:[1,0]
	v_mul_f32_e32 v216, v211, v210
	v_mul_f32_e32 v217, v213, v212
	v_mul_f32_e32 v0, v216, v217
	v_rcp_f32_e32 v203, v0
	v_cvt_pk_bf16_f32 v205, v206, v207
	v_mul_f32_e32 v0, v217, v203
	v_mul_f32_e32 v216, v216, v203
	v_pk_mul_f32 v[210:211], v[210:211], v[0:1] op_sel_hi:[1,0]
	v_pk_mul_f32 v[212:213], v[212:213], v[216:217] op_sel_hi:[1,0]
	v_pk_mul_f32 v[212:213], v[68:69], v[212:213]
	v_pk_mul_f32 v[210:211], v[66:67], v[210:211]
	v_cvt_pk_bf16_f32 v207, v212, v213
	v_cvt_pk_bf16_f32 v206, v210, v211
	v_add_u32_e32 v0, 0x80, v202
	global_store_dwordx4 v[208:209], v[204:207], off
	v_ashrrev_i32_e32 v203, 31, v0
	v_mul_lo_u32 v203, s56, v203
	v_pk_mul_f32 v[206:207], v[62:63], s[8:9] op_sel_hi:[1,0]
	v_mul_lo_u32 v204, s57, v0
	v_mad_u64_u32 v[208:209], s[10:11], s56, v0, 0
	v_min_f32_e32 v0, 0x41e6d4ca, v206
	v_add3_u32 v209, v209, v203, v204
	v_pk_mul_f32 v[204:205], v[64:65], s[8:9] op_sel_hi:[1,0]
	v_exp_f32_e32 v211, v0
	v_min_f32_e32 v0, 0x41e6d4ca, v207
	v_exp_f32_e32 v210, v0
	v_min_f32_e32 v0, 0x41e6d4ca, v204
	v_exp_f32_e32 v207, v0
	v_min_f32_e32 v0, 0x41e6d4ca, v205
	v_exp_f32_e32 v206, v0
	v_pk_add_f32 v[204:205], v[210:211], 1.0 op_sel_hi:[1,0]
	v_lshlrev_b64 v[208:209], 1, v[208:209]
	v_pk_add_f32 v[206:207], v[206:207], 1.0 op_sel_hi:[1,0]
	v_mul_f32_e32 v210, v205, v204
	v_mul_f32_e32 v211, v207, v206
	v_mul_f32_e32 v0, v210, v211
	v_rcp_f32_e32 v203, v0
	s_nop 0
	v_mul_f32_e32 v210, v210, v203
	v_pk_mul_f32 v[206:207], v[206:207], v[210:211] op_sel_hi:[1,0]
	v_mul_f32_e32 v0, v211, v203
	v_pk_mul_f32 v[206:207], v[64:65], v[206:207]
	v_pk_mul_f32 v[212:213], v[58:59], s[8:9] op_sel_hi:[1,0]
	v_pk_mul_f32 v[204:205], v[204:205], v[0:1] op_sel_hi:[1,0]
	v_min_f32_e32 v0, 0x41e6d4ca, v212
	v_pk_mul_f32 v[204:205], v[62:63], v[204:205]
	v_pk_mul_f32 v[210:211], v[60:61], s[8:9] op_sel_hi:[1,0]
	v_exp_f32_e32 v217, v0
	v_min_f32_e32 v0, 0x41e6d4ca, v213
	v_exp_f32_e32 v216, v0
	v_min_f32_e32 v0, 0x41e6d4ca, v210
	v_exp_f32_e32 v213, v0
	v_min_f32_e32 v0, 0x41e6d4ca, v211
	v_exp_f32_e32 v212, v0
	v_pk_add_f32 v[210:211], v[216:217], 1.0 op_sel_hi:[1,0]
	v_cvt_pk_bf16_f32 v204, v204, v205
	v_pk_add_f32 v[212:213], v[212:213], 1.0 op_sel_hi:[1,0]
	v_mul_f32_e32 v216, v211, v210
	v_mul_f32_e32 v217, v213, v212
	v_mul_f32_e32 v0, v216, v217
	v_rcp_f32_e32 v203, v0
	v_cvt_pk_bf16_f32 v205, v206, v207
	v_mul_f32_e32 v0, v217, v203
	v_mul_f32_e32 v216, v216, v203
	v_pk_mul_f32 v[210:211], v[210:211], v[0:1] op_sel_hi:[1,0]
	v_pk_mul_f32 v[212:213], v[212:213], v[216:217] op_sel_hi:[1,0]
	v_pk_mul_f32 v[212:213], v[60:61], v[212:213]
	v_pk_mul_f32 v[210:211], v[58:59], v[210:211]
	v_cvt_pk_bf16_f32 v207, v212, v213
	v_cvt_pk_bf16_f32 v206, v210, v211
	v_lshl_add_u64 v[210:211], v[174:175], 0, v[208:209]
	global_store_dwordx4 v[210:211], v[204:207], off
	v_lshl_add_u64 v[208:209], v[176:177], 0, v[208:209]
	s_nop 0
	v_pk_mul_f32 v[206:207], v[54:55], s[8:9] op_sel_hi:[1,0]
	v_pk_mul_f32 v[204:205], v[56:57], s[8:9] op_sel_hi:[1,0]
	v_min_f32_e32 v0, 0x41e6d4ca, v206
	v_exp_f32_e32 v211, v0
	v_min_f32_e32 v0, 0x41e6d4ca, v207
	v_exp_f32_e32 v210, v0
	v_min_f32_e32 v0, 0x41e6d4ca, v204
	v_exp_f32_e32 v207, v0
	v_min_f32_e32 v0, 0x41e6d4ca, v205
	v_exp_f32_e32 v206, v0
	v_pk_add_f32 v[204:205], v[210:211], 1.0 op_sel_hi:[1,0]
	v_pk_add_f32 v[206:207], v[206:207], 1.0 op_sel_hi:[1,0]
	v_mul_f32_e32 v210, v205, v204
	v_mul_f32_e32 v211, v207, v206
	v_mul_f32_e32 v0, v210, v211
	v_rcp_f32_e32 v203, v0
	s_nop 0
	v_mul_f32_e32 v210, v210, v203
	v_pk_mul_f32 v[206:207], v[206:207], v[210:211] op_sel_hi:[1,0]
	v_mul_f32_e32 v0, v211, v203
	v_pk_mul_f32 v[206:207], v[56:57], v[206:207]
	v_pk_mul_f32 v[212:213], v[50:51], s[8:9] op_sel_hi:[1,0]
	v_pk_mul_f32 v[204:205], v[204:205], v[0:1] op_sel_hi:[1,0]
	v_min_f32_e32 v0, 0x41e6d4ca, v212
	v_pk_mul_f32 v[204:205], v[54:55], v[204:205]
	v_pk_mul_f32 v[210:211], v[52:53], s[8:9] op_sel_hi:[1,0]
	v_exp_f32_e32 v217, v0
	v_min_f32_e32 v0, 0x41e6d4ca, v213
	v_exp_f32_e32 v216, v0
	v_min_f32_e32 v0, 0x41e6d4ca, v210
	v_exp_f32_e32 v213, v0
	v_min_f32_e32 v0, 0x41e6d4ca, v211
	v_exp_f32_e32 v212, v0
	v_pk_add_f32 v[210:211], v[216:217], 1.0 op_sel_hi:[1,0]
	v_cvt_pk_bf16_f32 v204, v204, v205
	v_pk_add_f32 v[212:213], v[212:213], 1.0 op_sel_hi:[1,0]
	v_mul_f32_e32 v216, v211, v210
	v_mul_f32_e32 v217, v213, v212
	v_mul_f32_e32 v0, v216, v217
	v_rcp_f32_e32 v203, v0
	v_cvt_pk_bf16_f32 v205, v206, v207
	v_mul_f32_e32 v0, v217, v203
	v_mul_f32_e32 v216, v216, v203
	v_pk_mul_f32 v[210:211], v[210:211], v[0:1] op_sel_hi:[1,0]
	v_pk_mul_f32 v[212:213], v[212:213], v[216:217] op_sel_hi:[1,0]
	v_pk_mul_f32 v[212:213], v[52:53], v[212:213]
	v_pk_mul_f32 v[210:211], v[50:51], v[210:211]
	v_cvt_pk_bf16_f32 v207, v212, v213
	v_cvt_pk_bf16_f32 v206, v210, v211
	v_add_u32_e32 v0, 0x90, v202
	global_store_dwordx4 v[208:209], v[204:207], off
	v_ashrrev_i32_e32 v203, 31, v0
	v_mul_lo_u32 v203, s56, v203
	v_pk_mul_f32 v[206:207], v[46:47], s[8:9] op_sel_hi:[1,0]
	v_mul_lo_u32 v204, s57, v0
	v_mad_u64_u32 v[208:209], s[10:11], s56, v0, 0
	v_min_f32_e32 v0, 0x41e6d4ca, v206
	v_add3_u32 v209, v209, v203, v204
	v_pk_mul_f32 v[204:205], v[48:49], s[8:9] op_sel_hi:[1,0]
	v_exp_f32_e32 v211, v0
	v_min_f32_e32 v0, 0x41e6d4ca, v207
	v_exp_f32_e32 v210, v0
	v_min_f32_e32 v0, 0x41e6d4ca, v204
	v_exp_f32_e32 v207, v0
	v_min_f32_e32 v0, 0x41e6d4ca, v205
	v_exp_f32_e32 v206, v0
	v_pk_add_f32 v[204:205], v[210:211], 1.0 op_sel_hi:[1,0]
	v_lshlrev_b64 v[208:209], 1, v[208:209]
	v_pk_add_f32 v[206:207], v[206:207], 1.0 op_sel_hi:[1,0]
	v_mul_f32_e32 v210, v205, v204
	v_mul_f32_e32 v211, v207, v206
	v_mul_f32_e32 v0, v210, v211
	v_rcp_f32_e32 v203, v0
	s_nop 0
	v_mul_f32_e32 v210, v210, v203
	v_pk_mul_f32 v[206:207], v[206:207], v[210:211] op_sel_hi:[1,0]
	v_mul_f32_e32 v0, v211, v203
	v_pk_mul_f32 v[206:207], v[48:49], v[206:207]
	v_pk_mul_f32 v[212:213], v[42:43], s[8:9] op_sel_hi:[1,0]
	v_pk_mul_f32 v[204:205], v[204:205], v[0:1] op_sel_hi:[1,0]
	v_min_f32_e32 v0, 0x41e6d4ca, v212
	v_pk_mul_f32 v[204:205], v[46:47], v[204:205]
	v_pk_mul_f32 v[210:211], v[44:45], s[8:9] op_sel_hi:[1,0]
	v_exp_f32_e32 v217, v0
	v_min_f32_e32 v0, 0x41e6d4ca, v213
	v_exp_f32_e32 v216, v0
	v_min_f32_e32 v0, 0x41e6d4ca, v210
	v_exp_f32_e32 v213, v0
	v_min_f32_e32 v0, 0x41e6d4ca, v211
	v_exp_f32_e32 v212, v0
	v_pk_add_f32 v[210:211], v[216:217], 1.0 op_sel_hi:[1,0]
	v_cvt_pk_bf16_f32 v204, v204, v205
	v_pk_add_f32 v[212:213], v[212:213], 1.0 op_sel_hi:[1,0]
	v_mul_f32_e32 v216, v211, v210
	v_mul_f32_e32 v217, v213, v212
	v_mul_f32_e32 v0, v216, v217
	v_rcp_f32_e32 v203, v0
	v_cvt_pk_bf16_f32 v205, v206, v207
	v_mul_f32_e32 v0, v217, v203
	v_mul_f32_e32 v216, v216, v203
	v_pk_mul_f32 v[210:211], v[210:211], v[0:1] op_sel_hi:[1,0]
	v_pk_mul_f32 v[212:213], v[212:213], v[216:217] op_sel_hi:[1,0]
	v_pk_mul_f32 v[212:213], v[44:45], v[212:213]
	v_pk_mul_f32 v[210:211], v[42:43], v[210:211]
	v_cvt_pk_bf16_f32 v207, v212, v213
	v_cvt_pk_bf16_f32 v206, v210, v211
	v_lshl_add_u64 v[210:211], v[174:175], 0, v[208:209]
	global_store_dwordx4 v[210:211], v[204:207], off
	v_lshl_add_u64 v[208:209], v[176:177], 0, v[208:209]
	s_nop 0
	v_pk_mul_f32 v[206:207], v[38:39], s[8:9] op_sel_hi:[1,0]
	v_pk_mul_f32 v[204:205], v[40:41], s[8:9] op_sel_hi:[1,0]
	v_min_f32_e32 v0, 0x41e6d4ca, v206
	v_exp_f32_e32 v211, v0
	v_min_f32_e32 v0, 0x41e6d4ca, v207
	v_exp_f32_e32 v210, v0
	v_min_f32_e32 v0, 0x41e6d4ca, v204
	v_exp_f32_e32 v207, v0
	v_min_f32_e32 v0, 0x41e6d4ca, v205
	v_exp_f32_e32 v206, v0
	v_pk_add_f32 v[204:205], v[210:211], 1.0 op_sel_hi:[1,0]
	v_pk_add_f32 v[206:207], v[206:207], 1.0 op_sel_hi:[1,0]
	v_mul_f32_e32 v210, v205, v204
	v_mul_f32_e32 v211, v207, v206
	v_mul_f32_e32 v0, v210, v211
	v_rcp_f32_e32 v203, v0
	s_nop 0
	v_mul_f32_e32 v210, v210, v203
	v_pk_mul_f32 v[206:207], v[206:207], v[210:211] op_sel_hi:[1,0]
	v_mul_f32_e32 v0, v211, v203
	v_pk_mul_f32 v[206:207], v[40:41], v[206:207]
	v_pk_mul_f32 v[212:213], v[34:35], s[8:9] op_sel_hi:[1,0]
	v_pk_mul_f32 v[204:205], v[204:205], v[0:1] op_sel_hi:[1,0]
	v_min_f32_e32 v0, 0x41e6d4ca, v212
	v_pk_mul_f32 v[204:205], v[38:39], v[204:205]
	v_pk_mul_f32 v[210:211], v[36:37], s[8:9] op_sel_hi:[1,0]
	v_exp_f32_e32 v217, v0
	v_min_f32_e32 v0, 0x41e6d4ca, v213
	v_exp_f32_e32 v216, v0
	v_min_f32_e32 v0, 0x41e6d4ca, v210
	v_exp_f32_e32 v213, v0
	v_min_f32_e32 v0, 0x41e6d4ca, v211
	v_exp_f32_e32 v212, v0
	v_pk_add_f32 v[210:211], v[216:217], 1.0 op_sel_hi:[1,0]
	v_cvt_pk_bf16_f32 v204, v204, v205
	v_pk_add_f32 v[212:213], v[212:213], 1.0 op_sel_hi:[1,0]
	v_mul_f32_e32 v216, v211, v210
	v_mul_f32_e32 v217, v213, v212
	v_mul_f32_e32 v0, v216, v217
	v_rcp_f32_e32 v203, v0
	v_cvt_pk_bf16_f32 v205, v206, v207
	v_mul_f32_e32 v0, v217, v203
	v_mul_f32_e32 v216, v216, v203
	v_pk_mul_f32 v[210:211], v[210:211], v[0:1] op_sel_hi:[1,0]
	v_pk_mul_f32 v[212:213], v[212:213], v[216:217] op_sel_hi:[1,0]
	v_pk_mul_f32 v[212:213], v[36:37], v[212:213]
	v_pk_mul_f32 v[210:211], v[34:35], v[210:211]
	v_cvt_pk_bf16_f32 v207, v212, v213
	v_cvt_pk_bf16_f32 v206, v210, v211
	v_add_u32_e32 v0, 0xa0, v202
	global_store_dwordx4 v[208:209], v[204:207], off
	v_ashrrev_i32_e32 v203, 31, v0
	v_mul_lo_u32 v203, s56, v203
	v_pk_mul_f32 v[206:207], v[30:31], s[8:9] op_sel_hi:[1,0]
	v_mul_lo_u32 v204, s57, v0
	v_mad_u64_u32 v[208:209], s[10:11], s56, v0, 0
	v_min_f32_e32 v0, 0x41e6d4ca, v206
	v_add3_u32 v209, v209, v203, v204
	v_pk_mul_f32 v[204:205], v[32:33], s[8:9] op_sel_hi:[1,0]
	v_exp_f32_e32 v211, v0
	v_min_f32_e32 v0, 0x41e6d4ca, v207
	v_exp_f32_e32 v210, v0
	v_min_f32_e32 v0, 0x41e6d4ca, v204
	v_exp_f32_e32 v207, v0
	v_min_f32_e32 v0, 0x41e6d4ca, v205
	v_exp_f32_e32 v206, v0
	v_pk_add_f32 v[204:205], v[210:211], 1.0 op_sel_hi:[1,0]
	v_lshlrev_b64 v[208:209], 1, v[208:209]
	v_pk_add_f32 v[206:207], v[206:207], 1.0 op_sel_hi:[1,0]
	v_mul_f32_e32 v210, v205, v204
	v_mul_f32_e32 v211, v207, v206
	v_mul_f32_e32 v0, v210, v211
	v_rcp_f32_e32 v203, v0
	v_lshl_add_u64 v[176:177], v[176:177], 0, v[208:209]
	v_mul_f32_e32 v210, v210, v203
	v_pk_mul_f32 v[206:207], v[206:207], v[210:211] op_sel_hi:[1,0]
	v_mul_f32_e32 v0, v211, v203
	v_pk_mul_f32 v[206:207], v[32:33], v[206:207]
	v_pk_mul_f32 v[212:213], v[26:27], s[8:9] op_sel_hi:[1,0]
	v_pk_mul_f32 v[204:205], v[204:205], v[0:1] op_sel_hi:[1,0]
	v_min_f32_e32 v0, 0x41e6d4ca, v212
	v_pk_mul_f32 v[204:205], v[30:31], v[204:205]
	v_pk_mul_f32 v[210:211], v[28:29], s[8:9] op_sel_hi:[1,0]
	v_exp_f32_e32 v217, v0
	v_min_f32_e32 v0, 0x41e6d4ca, v213
	v_exp_f32_e32 v216, v0
	v_min_f32_e32 v0, 0x41e6d4ca, v210
	v_exp_f32_e32 v213, v0
	v_min_f32_e32 v0, 0x41e6d4ca, v211
	v_exp_f32_e32 v212, v0
	v_pk_add_f32 v[210:211], v[216:217], 1.0 op_sel_hi:[1,0]
	v_cvt_pk_bf16_f32 v204, v204, v205
	v_pk_add_f32 v[212:213], v[212:213], 1.0 op_sel_hi:[1,0]
	v_mul_f32_e32 v216, v211, v210
	v_mul_f32_e32 v217, v213, v212
	v_mul_f32_e32 v0, v216, v217
	v_rcp_f32_e32 v203, v0
	v_cvt_pk_bf16_f32 v205, v206, v207
	v_mul_f32_e32 v0, v217, v203
	v_mul_f32_e32 v216, v216, v203
	v_pk_mul_f32 v[210:211], v[210:211], v[0:1] op_sel_hi:[1,0]
	v_pk_mul_f32 v[212:213], v[212:213], v[216:217] op_sel_hi:[1,0]
	v_pk_mul_f32 v[212:213], v[28:29], v[212:213]
	v_pk_mul_f32 v[210:211], v[26:27], v[210:211]
	v_cvt_pk_bf16_f32 v207, v212, v213
	v_cvt_pk_bf16_f32 v206, v210, v211
	v_lshl_add_u64 v[210:211], v[174:175], 0, v[208:209]
	global_store_dwordx4 v[210:211], v[204:207], off
	s_nop 1
	v_pk_mul_f32 v[206:207], v[22:23], s[8:9] op_sel_hi:[1,0]
	v_pk_mul_f32 v[204:205], v[24:25], s[8:9] op_sel_hi:[1,0]
	v_min_f32_e32 v0, 0x41e6d4ca, v206
	v_exp_f32_e32 v211, v0
	v_min_f32_e32 v0, 0x41e6d4ca, v207
	v_exp_f32_e32 v210, v0
	v_min_f32_e32 v0, 0x41e6d4ca, v204
	v_exp_f32_e32 v207, v0
	v_min_f32_e32 v0, 0x41e6d4ca, v205
	v_exp_f32_e32 v206, v0
	v_pk_add_f32 v[204:205], v[210:211], 1.0 op_sel_hi:[1,0]
	v_pk_add_f32 v[206:207], v[206:207], 1.0 op_sel_hi:[1,0]
	v_mul_f32_e32 v210, v205, v204
	v_mul_f32_e32 v211, v207, v206
	v_mul_f32_e32 v0, v210, v211
	v_rcp_f32_e32 v203, v0
	s_nop 0
	v_mul_f32_e32 v210, v210, v203
	v_pk_mul_f32 v[206:207], v[206:207], v[210:211] op_sel_hi:[1,0]
	v_mul_f32_e32 v0, v211, v203
	v_pk_mul_f32 v[206:207], v[24:25], v[206:207]
	v_pk_mul_f32 v[212:213], v[18:19], s[8:9] op_sel_hi:[1,0]
	v_pk_mul_f32 v[204:205], v[204:205], v[0:1] op_sel_hi:[1,0]
	v_min_f32_e32 v0, 0x41e6d4ca, v212
	v_pk_mul_f32 v[204:205], v[22:23], v[204:205]
	v_pk_mul_f32 v[210:211], v[20:21], s[8:9] op_sel_hi:[1,0]
	v_exp_f32_e32 v217, v0
	v_min_f32_e32 v0, 0x41e6d4ca, v213
	v_exp_f32_e32 v216, v0
	v_min_f32_e32 v0, 0x41e6d4ca, v210
	v_exp_f32_e32 v213, v0
	v_min_f32_e32 v0, 0x41e6d4ca, v211
	v_exp_f32_e32 v212, v0
	v_pk_add_f32 v[210:211], v[216:217], 1.0 op_sel_hi:[1,0]
	v_cvt_pk_bf16_f32 v204, v204, v205
	v_pk_add_f32 v[212:213], v[212:213], 1.0 op_sel_hi:[1,0]
	v_mul_f32_e32 v216, v211, v210
	v_mul_f32_e32 v217, v213, v212
	v_mul_f32_e32 v0, v216, v217
	v_rcp_f32_e32 v203, v0
	v_cvt_pk_bf16_f32 v205, v206, v207
	v_mul_f32_e32 v0, v217, v203
	v_mul_f32_e32 v216, v216, v203
	v_pk_mul_f32 v[210:211], v[210:211], v[0:1] op_sel_hi:[1,0]
	v_pk_mul_f32 v[212:213], v[212:213], v[216:217] op_sel_hi:[1,0]
	v_pk_mul_f32 v[212:213], v[20:21], v[212:213]
	v_pk_mul_f32 v[210:211], v[18:19], v[210:211]
	v_cvt_pk_bf16_f32 v207, v212, v213
	v_cvt_pk_bf16_f32 v206, v210, v211
	v_add_u32_e32 v0, 0xb0, v202
	global_store_dwordx4 v[176:177], v[204:207], off
	v_ashrrev_i32_e32 v176, 31, v0
	v_mul_lo_u32 v203, s56, v176
	v_pk_mul_f32 v[206:207], v[14:15], s[8:9] op_sel_hi:[1,0]
	v_mul_lo_u32 v204, s57, v0
	v_mad_u64_u32 v[176:177], s[10:11], s56, v0, 0
	v_min_f32_e32 v0, 0x41e6d4ca, v206
	v_add3_u32 v177, v177, v203, v204
	v_pk_mul_f32 v[204:205], v[16:17], s[8:9] op_sel_hi:[1,0]
	v_exp_f32_e32 v209, v0
	v_min_f32_e32 v0, 0x41e6d4ca, v207
	v_exp_f32_e32 v208, v0
	v_min_f32_e32 v0, 0x41e6d4ca, v204
	v_exp_f32_e32 v207, v0
	v_min_f32_e32 v0, 0x41e6d4ca, v205
	v_exp_f32_e32 v206, v0
	v_pk_add_f32 v[204:205], v[208:209], 1.0 op_sel_hi:[1,0]
	v_pk_add_f32 v[206:207], v[206:207], 1.0 op_sel_hi:[1,0]
	v_mul_f32_e32 v208, v205, v204
	v_mul_f32_e32 v209, v207, v206
	v_mul_f32_e32 v0, v208, v209
	v_rcp_f32_e32 v203, v0
	s_nop 0
	v_mul_f32_e32 v208, v208, v203
	v_pk_mul_f32 v[206:207], v[206:207], v[208:209] op_sel_hi:[1,0]
	v_mul_f32_e32 v0, v209, v203
	v_pk_mul_f32 v[144:145], v[16:17], v[206:207]
	v_pk_mul_f32 v[206:207], v[10:11], s[8:9] op_sel_hi:[1,0]
	v_pk_mul_f32 v[204:205], v[204:205], v[0:1] op_sel_hi:[1,0]
	v_min_f32_e32 v0, 0x41e6d4ca, v206
	v_pk_mul_f32 v[142:143], v[14:15], v[204:205]
	v_pk_mul_f32 v[204:205], v[12:13], s[8:9] op_sel_hi:[1,0]
	v_exp_f32_e32 v209, v0
	v_min_f32_e32 v0, 0x41e6d4ca, v207
	v_exp_f32_e32 v208, v0
	v_min_f32_e32 v0, 0x41e6d4ca, v204
	v_exp_f32_e32 v207, v0
	v_min_f32_e32 v0, 0x41e6d4ca, v205
	v_exp_f32_e32 v206, v0
	v_pk_add_f32 v[204:205], v[208:209], 1.0 op_sel_hi:[1,0]
	s_nop 0
	v_mov_b32_e32 v208, v205
	v_pk_add_f32 v[206:207], v[206:207], 1.0 op_sel_hi:[1,0]
	v_mov_b32_e32 v210, v204
	v_mov_b32_e32 v209, v207
	v_mov_b32_e32 v211, v206
	v_pk_mul_f32 v[208:209], v[208:209], v[210:211]
	s_nop 0
	v_mul_f32_e32 v0, v208, v209
	v_rcp_f32_e32 v203, v0
	s_mov_b64 s[10:11], 0
	v_mul_f32_e32 v0, v209, v203
	v_mul_f32_e32 v208, v208, v203
	v_pk_mul_f32 v[204:205], v[204:205], v[0:1] op_sel_hi:[1,0]
	v_pk_mul_f32 v[206:207], v[206:207], v[208:209] op_sel_hi:[1,0]
	s_nop 0
	v_pk_mul_f32 v[206:207], v[12:13], v[206:207]
	v_pk_mul_f32 v[140:141], v[10:11], v[204:205]
	v_cvt_pk_bf16_f32 v138, v142, v143
	v_cvt_pk_bf16_f32 v139, v144, v145
	v_cvt_pk_bf16_f32 v140, v140, v141
	v_cvt_pk_bf16_f32 v141, v206, v207
	v_lshl_add_u64 v[142:143], v[176:177], 1, v[174:175]
	global_store_dwordx4 v[142:143], v[138:141], off
	s_nop 1
	v_pk_mul_f32 v[140:141], v[6:7], s[8:9] op_sel_hi:[1,0]
	v_pk_mul_f32 v[138:139], v[8:9], s[8:9] op_sel_hi:[1,0]
	v_min_f32_e32 v0, 0x41e6d4ca, v140
	v_exp_f32_e32 v143, v0
	v_min_f32_e32 v0, 0x41e6d4ca, v141
	v_exp_f32_e32 v142, v0
	v_min_f32_e32 v0, 0x41e6d4ca, v138
	v_exp_f32_e32 v141, v0
	v_min_f32_e32 v0, 0x41e6d4ca, v139
	v_exp_f32_e32 v140, v0
	v_pk_add_f32 v[138:139], v[142:143], 1.0 op_sel_hi:[1,0]
	v_pk_add_f32 v[140:141], v[140:141], 1.0 op_sel_hi:[1,0]
	v_mul_f32_e32 v142, v139, v138
	v_mul_f32_e32 v143, v141, v140
	s_nop 0
	v_mul_f32_e32 v0, v142, v143
	v_rcp_f32_e32 v144, v0
	s_nop 0
	v_mul_f32_e32 v0, v143, v144
	v_pk_mul_f32 v[138:139], v[138:139], v[0:1] op_sel_hi:[1,0]
	v_mul_f32_e32 v142, v142, v144
	v_pk_mul_f32 v[134:135], v[6:7], v[138:139]
	v_pk_mul_f32 v[138:139], v[2:3], s[8:9] op_sel_hi:[1,0]
	v_pk_mul_f32 v[140:141], v[140:141], v[142:143] op_sel_hi:[1,0]
	v_min_f32_e32 v0, 0x41e6d4ca, v138
	v_pk_mul_f32 v[140:141], v[8:9], v[140:141]
	v_pk_mul_f32 v[136:137], v[4:5], s[8:9] op_sel_hi:[1,0]
	v_exp_f32_e32 v143, v0
	v_min_f32_e32 v0, 0x41e6d4ca, v139
	v_exp_f32_e32 v142, v0
	v_min_f32_e32 v0, 0x41e6d4ca, v136
	v_exp_f32_e32 v139, v0
	v_min_f32_e32 v0, 0x41e6d4ca, v137
	v_exp_f32_e32 v138, v0
	v_pk_add_f32 v[136:137], v[142:143], 1.0 op_sel_hi:[1,0]
	v_pk_add_f32 v[138:139], v[138:139], 1.0 op_sel_hi:[1,0]
	v_mul_f32_e32 v142, v137, v136
	v_mul_f32_e32 v143, v139, v138
	s_nop 0
	v_mul_f32_e32 v0, v142, v143
	v_rcp_f32_e32 v144, v0
	s_nop 0
	v_mul_f32_e32 v0, v143, v144
	v_mul_f32_e32 v142, v142, v144
	v_pk_mul_f32 v[144:145], v[136:137], v[0:1] op_sel_hi:[1,0]
	v_pk_mul_f32 v[136:137], v[138:139], v[142:143] op_sel_hi:[1,0]
	s_nop 0
	v_pk_mul_f32 v[136:137], v[4:5], v[136:137]
	v_pk_mul_f32 v[132:133], v[2:3], v[144:145]
	v_cvt_pk_bf16_f32 v130, v134, v135
	v_cvt_pk_bf16_f32 v131, v140, v141
	v_cvt_pk_bf16_f32 v132, v132, v133
